# non-temporal hint on the once-read f32 weight loads of the transpose items
# speedup vs baseline: 1.0153x; 1.0153x over previous
; #define LAS __attribute__((address_space(3)))
; #define LDS_WAIT() asm volatile("s_waitcnt lgkmcnt(0)" ::: "memory")
; __device__ __forceinline__ unsigned pk2(float lo, float hi) { return f2bf(lo) | (f2bf(hi) << 16); }
; __device__ __forceinline__ void transpose_item(const float* __restrict__ W, int ldw, int k0, int c0, bf16* WT, int K, int drow0, LAS float* scr, int lane) {
;     { const int kr = lane >> 3, n4 = lane & 7;
;       f32x4 v[8];
; #pragma unroll
;       for (int i = 0; i < 8; ++i) v[i] = *(const f32x4*)(W + (size_t)(k0 + 8 * i + kr) * ldw + c0 + 4 * n4);
; #pragma unroll
;       for (int i = 0; i < 8; ++i) { LAS float* p = scr + (8 * i + kr) * 33 + 4 * n4; p[0] = v[i].x; p[1] = v[i].y; p[2] = v[i].z; p[3] = v[i].w; } }
;     LDS_WAIT(); asm volatile("" ::: "memory");
;     const int c = lane & 7;
; #pragma unroll
;     for (int j = 0; j < 4; ++j) { const int n = (lane >> 3) + 8 * j; const LAS float* s = scr + (8 * c) * 33 + n;
;         v4u o; o.x = pk2(s[0 * 33], s[1 * 33]); o.y = pk2(s[2 * 33], s[3 * 33]); o.z = pk2(s[4 * 33], s[5 * 33]); o.w = pk2(s[6 * 33], s[7 * 33]);
;         *(v4u*)(WT + (size_t)(drow0 + n) * K + k0 + 8 * c) = o; }
;     LDS_WAIT(); asm volatile("" ::: "memory");
.LBB0_104:
	s_andn2_b64 vcc, exec, s[12:13]
	s_cbranch_vccnz .LBB0_106
	s_lshl_b32 s0, s3, 1
	s_and_b32 s0, s0, 0x7fc0
	s_add_i32 s6, s0, 0xffff9800
	s_lshl_b32 s0, s3, 5
	s_and_b32 s0, s0, 0x3e0
	s_load_dwordx2 s[12:13], s[96:97], 0x78
	s_waitcnt lgkmcnt(0)
	s_lshl_b32 s1, s0, 2
	s_add_u32 s12, s12, s1
	v_or_b32_e32 v2, s6, v77
	s_addc_u32 s13, s13, 0
	v_lshl_add_u64 v[0:1], s[12:13], 0, v[56:57]
	v_lshlrev_b32_e32 v2, 10, v2
	v_mov_b32_e32 v3, v57
	v_lshl_add_u64 v[28:29], v[2:3], 2, v[0:1]
	v_add_co_u32_e32 v4, vcc, s29, v28
	v_lshl_add_u64 v[32:33], s[6:7], 1, v[60:61]
	s_nop 0
	v_addc_co_u32_e32 v5, vcc, 0, v29, vcc
	v_add_co_u32_e32 v8, vcc, s30, v28
	global_load_dwordx4 v[0:3], v[28:29], off nt
	s_nop 0
	global_load_dwordx4 v[4:7], v[4:5], off nt
	v_addc_co_u32_e32 v9, vcc, 0, v29, vcc
	v_add_co_u32_e32 v12, vcc, s31, v28
	s_nop 1
	v_addc_co_u32_e32 v13, vcc, 0, v29, vcc
	v_add_co_u32_e32 v16, vcc, s33, v28
	global_load_dwordx4 v[8:11], v[8:9], off nt
	s_nop 0
	global_load_dwordx4 v[12:15], v[12:13], off nt
	v_addc_co_u32_e32 v17, vcc, 0, v29, vcc
	v_add_co_u32_e32 v20, vcc, s34, v28
	s_nop 1
	v_addc_co_u32_e32 v21, vcc, 0, v29, vcc
	global_load_dwordx4 v[16:19], v[16:17], off nt
	s_nop 0
	global_load_dwordx4 v[20:23], v[20:21], off nt
	v_add_co_u32_e32 v24, vcc, s35, v28
	s_nop 1
	v_addc_co_u32_e32 v25, vcc, 0, v29, vcc
	global_load_dwordx4 v[24:27], v[24:25], off nt
	v_add_co_u32_e32 v28, vcc, s36, v28
	s_nop 1
	v_addc_co_u32_e32 v29, vcc, 0, v29, vcc
	global_load_dwordx4 v[28:31], v[28:29], off nt
	s_waitcnt vmcnt(7)
	ds_write2_b32 v82, v0, v1 offset1:1
	ds_write2_b32 v82, v2, v3 offset0:2 offset1:3
	s_waitcnt vmcnt(6)
	ds_write2_b32 v83, v4, v5 offset1:1
	ds_write2_b32 v84, v6, v7 offset1:1
	s_waitcnt vmcnt(5)
	ds_write2_b32 v85, v8, v9 offset1:1
	ds_write2_b32 v86, v10, v11 offset1:1
	s_waitcnt vmcnt(4)
	ds_write2_b32 v87, v12, v13 offset1:1
	ds_write2_b32 v88, v14, v15 offset1:1
	s_waitcnt vmcnt(3)
	ds_write2_b32 v89, v16, v17 offset1:1
	ds_write2_b32 v90, v18, v19 offset1:1
	s_waitcnt vmcnt(2)
	ds_write2_b32 v91, v20, v21 offset1:1
	ds_write2_b32 v92, v22, v23 offset1:1
	s_waitcnt vmcnt(1)
	ds_write2_b32 v93, v24, v25 offset1:1
	ds_write2_b32 v94, v26, v27 offset1:1
	s_waitcnt vmcnt(0)
	ds_write2_b32 v95, v28, v29 offset1:1
	ds_write2_b32 v96, v30, v31 offset1:1
	s_waitcnt lgkmcnt(0)
	ds_read2_b32 v[4:5], v81 offset0:33 offset1:41
	ds_read2_b32 v[6:7], v81 offset1:8
	ds_read2_b32 v[8:9], v81 offset0:66 offset1:74
	ds_read2_b32 v[10:11], v81 offset0:99 offset1:107
	ds_read2_b32 v[12:13], v81 offset0:132 offset1:140
	ds_read2_b32 v[14:15], v81 offset0:165 offset1:173
	ds_read2_b32 v[16:17], v81 offset0:198 offset1:206
	ds_read2_b32 v[18:19], v81 offset0:231 offset1:239
	s_waitcnt lgkmcnt(6)
	v_bfe_u32 v0, v6, 16, 1
	v_bfe_u32 v1, v4, 16, 1
	s_waitcnt lgkmcnt(5)
	v_bfe_u32 v2, v8, 16, 1
	s_waitcnt lgkmcnt(3)
	v_bfe_u32 v20, v12, 16, 1
	v_bfe_u32 v3, v10, 16, 1
	s_waitcnt lgkmcnt(2)
	v_bfe_u32 v21, v14, 16, 1
	v_add3_u32 v0, v6, v0, s37
	v_add3_u32 v1, v4, v1, s37
	v_add3_u32 v2, v8, v2, s37
	v_add3_u32 v4, v12, v20, s37
	s_waitcnt lgkmcnt(1)
	v_bfe_u32 v22, v16, 16, 1
	v_add3_u32 v3, v10, v3, s37
	v_add3_u32 v6, v14, v21, s37
	v_lshrrev_b32_e32 v0, 16, v0
	v_lshrrev_b32_e32 v2, 16, v2
	v_lshrrev_b32_e32 v4, 16, v4
	s_waitcnt lgkmcnt(0)
	v_bfe_u32 v23, v18, 16, 1
	v_add3_u32 v8, v16, v22, s37
	v_and_or_b32 v0, v1, s38, v0
	v_and_or_b32 v1, v3, s38, v2
	v_and_or_b32 v2, v6, s38, v4
	v_or_b32_e32 v4, s0, v77
	v_add3_u32 v10, v18, v23, s37
	v_lshrrev_b32_e32 v8, 16, v8
	v_lshlrev_b32_e32 v20, 11, v4
	v_mov_b32_e32 v21, v57
	v_and_or_b32 v3, v10, s38, v8
	v_lshl_add_u64 v[20:21], v[32:33], 0, v[20:21]
	global_store_dwordx4 v[20:21], v[0:3], off
	v_bfe_u32 v4, v19, 16, 1
	v_add3_u32 v4, v19, v4, s37
	v_bfe_u32 v0, v7, 16, 1
	v_add3_u32 v0, v7, v0, s37
	v_bfe_u32 v1, v5, 16, 1
	v_lshrrev_b32_e32 v0, 16, v0
	v_add3_u32 v1, v5, v1, s37
	v_and_or_b32 v0, v1, s38, v0
	v_bfe_u32 v1, v9, 16, 1
	v_add3_u32 v1, v9, v1, s37
	v_bfe_u32 v2, v11, 16, 1
	v_lshrrev_b32_e32 v1, 16, v1
	v_add3_u32 v2, v11, v2, s37
	v_and_or_b32 v1, v2, s38, v1
	v_bfe_u32 v2, v13, 16, 1
	v_add3_u32 v2, v13, v2, s37
	v_bfe_u32 v3, v15, 16, 1
	v_lshrrev_b32_e32 v2, 16, v2
	v_add3_u32 v3, v15, v3, s37
	v_and_or_b32 v2, v3, s38, v2
	v_bfe_u32 v3, v17, 16, 1
	v_add3_u32 v3, v17, v3, s37
	v_lshrrev_b32_e32 v3, 16, v3
	v_and_or_b32 v3, v4, s38, v3
	v_or_b32_e32 v4, s0, v78
	v_lshlrev_b32_e32 v4, 11, v4
	v_mov_b32_e32 v5, v57
	ds_read2_b32 v[6:7], v81 offset0:16 offset1:24
	v_lshl_add_u64 v[4:5], v[32:33], 0, v[4:5]
	global_store_dwordx4 v[4:5], v[0:3], off
	ds_read2_b32 v[4:5], v81 offset0:49 offset1:57
	ds_read2_b32 v[8:9], v81 offset0:82 offset1:90
	ds_read2_b32 v[10:11], v81 offset0:115 offset1:123
	s_waitcnt lgkmcnt(3)
	v_bfe_u32 v0, v6, 16, 1
	v_add3_u32 v0, v6, v0, s37
	s_waitcnt lgkmcnt(2)
	v_bfe_u32 v1, v4, 16, 1
	ds_read2_b32 v[12:13], v81 offset0:148 offset1:156
	v_lshrrev_b32_e32 v0, 16, v0
	v_add3_u32 v1, v4, v1, s37
	ds_read2_b32 v[14:15], v81 offset0:181 offset1:189
	v_and_or_b32 v0, v1, s38, v0
	s_waitcnt lgkmcnt(3)
	v_bfe_u32 v1, v8, 16, 1
	v_add3_u32 v1, v8, v1, s37
	s_waitcnt lgkmcnt(2)
	v_bfe_u32 v2, v10, 16, 1
	ds_read2_b32 v[16:17], v81 offset0:214 offset1:222
	v_lshrrev_b32_e32 v1, 16, v1
	v_add3_u32 v2, v10, v2, s37
	ds_read2_b32 v[18:19], v81 offset0:247 offset1:255
	v_and_or_b32 v1, v2, s38, v1
	s_waitcnt lgkmcnt(3)
	v_bfe_u32 v2, v12, 16, 1
	v_add3_u32 v2, v12, v2, s37
	s_waitcnt lgkmcnt(2)
	v_bfe_u32 v3, v14, 16, 1
	v_lshrrev_b32_e32 v2, 16, v2
	v_add3_u32 v3, v14, v3, s37
	v_and_or_b32 v2, v3, s38, v2
	s_waitcnt lgkmcnt(1)
	v_bfe_u32 v3, v16, 16, 1
	v_add3_u32 v3, v16, v3, s37
	s_waitcnt lgkmcnt(0)
	v_bfe_u32 v4, v18, 16, 1
	v_lshrrev_b32_e32 v3, 16, v3
	v_add3_u32 v4, v18, v4, s37
	v_and_or_b32 v3, v4, s38, v3
	v_or_b32_e32 v4, s0, v79
	v_lshlrev_b32_e32 v20, 11, v4
	v_mov_b32_e32 v21, v57
	v_lshl_add_u64 v[20:21], v[32:33], 0, v[20:21]
	global_store_dwordx4 v[20:21], v[0:3], off
	v_bfe_u32 v4, v19, 16, 1
	v_add3_u32 v4, v19, v4, s37
	v_bfe_u32 v0, v7, 16, 1
	v_add3_u32 v0, v7, v0, s37
	v_bfe_u32 v1, v5, 16, 1
	v_lshrrev_b32_e32 v0, 16, v0
	v_add3_u32 v1, v5, v1, s37
	v_and_or_b32 v0, v1, s38, v0
	v_bfe_u32 v1, v9, 16, 1
	v_add3_u32 v1, v9, v1, s37
	v_bfe_u32 v2, v11, 16, 1
	v_lshrrev_b32_e32 v1, 16, v1
	v_add3_u32 v2, v11, v2, s37
	v_and_or_b32 v1, v2, s38, v1
	v_bfe_u32 v2, v13, 16, 1
	v_add3_u32 v2, v13, v2, s37
	v_bfe_u32 v3, v15, 16, 1
	v_lshrrev_b32_e32 v2, 16, v2
	v_add3_u32 v3, v15, v3, s37
	v_and_or_b32 v2, v3, s38, v2
	v_bfe_u32 v3, v17, 16, 1
	v_add3_u32 v3, v17, v3, s37
	v_lshrrev_b32_e32 v3, 16, v3
	v_and_or_b32 v3, v4, s38, v3
	v_or_b32_e32 v4, s0, v80
	v_lshlrev_b32_e32 v4, 11, v4
	v_mov_b32_e32 v5, v57
	v_lshl_add_u64 v[4:5], v[32:33], 0, v[4:5]
	global_store_dwordx4 v[4:5], v[0:3], off
	s_waitcnt lgkmcnt(0)

; #define LAS __attribute__((address_space(3)))
; #define LDS_WAIT() asm volatile("s_waitcnt lgkmcnt(0)" ::: "memory")
; __device__ __forceinline__ unsigned pk2(float lo, float hi) { return f2bf(lo) | (f2bf(hi) << 16); }
; #define ARG_IN(i) argp(i)
; __device__ __forceinline__ void transpose_item(const float* __restrict__ W, int ldw, int k0, int c0, bf16* WT, int K, int drow0, LAS float* scr, int lane) {
;     { const int kr = lane >> 3, n4 = lane & 7;
;       f32x4 v[8];
; #pragma unroll
;       for (int i = 0; i < 8; ++i) v[i] = *(const f32x4*)(W + (size_t)(k0 + 8 * i + kr) * ldw + c0 + 4 * n4);
; #pragma unroll
;       for (int i = 0; i < 8; ++i) { LAS float* p = scr + (8 * i + kr) * 33 + 4 * n4; p[0] = v[i].x; p[1] = v[i].y; p[2] = v[i].z; p[3] = v[i].w; } }
;     LDS_WAIT(); asm volatile("" ::: "memory");
;     const int c = lane & 7;
; #pragma unroll
;     for (int j = 0; j < 4; ++j) { const int n = (lane >> 3) + 8 * j; const LAS float* s = scr + (8 * c) * 33 + n;
;         v4u o; o.x = pk2(s[0 * 33], s[1 * 33]); o.y = pk2(s[2 * 33], s[3 * 33]); o.z = pk2(s[4 * 33], s[5 * 33]); o.w = pk2(s[6 * 33], s[7 * 33]);
;         *(v4u*)(WT + (size_t)(drow0 + n) * K + k0 + 8 * c) = o; }
;     LDS_WAIT(); asm volatile("" ::: "memory");
; __device__ __forceinline__ void weights_phase(int l, LAS unsigned char* lds, int vcu, int G, int wave, int lane) {
;     ...
;         } else if ((r -= IT_IN) < IT_BR) { const int n = (r / 256) * 2; r %= 256; const int kb = r / 32, nb = r % 32;
;             transpose_item(ARG_IN(14) + (size_t)(l * 3 + n) * 512 * 1024, 1024, 64 * kb, 32 * nb, WBR, 512, n * 1024 + 32 * nb, scr, lane);
.LBB0_107:
	s_andn2_b64 vcc, exec, s[12:13]
	s_cbranch_vccnz .LBB0_109
	s_add_i32 s0, s3, 0xffffce00
	s_lshr_b32 s0, s0, 7
	s_and_b32 s6, s0, 0x1fffffe
	s_lshl_b64 s[12:13], s[6:7], 21
	s_load_dwordx2 s[0:1], s[96:97], 0x70
	s_waitcnt lgkmcnt(0)
	s_add_u32 s12, s0, s12
	s_addc_u32 s1, s1, s13
	s_lshl_b32 s0, s3, 1
	s_and_b32 s14, s0, 0x1c0
	s_lshl_b32 s0, s3, 5
	s_and_b32 s13, s0, 0x3e0
	s_lshl_b32 s0, s6, 10
	s_or_b32 s0, s0, s13
	s_lshl_b32 s6, s13, 2
	s_add_u32 s12, s12, s6
	v_or_b32_e32 v2, s14, v77
	s_addc_u32 s13, s1, 0
	v_lshl_add_u64 v[0:1], s[12:13], 0, v[56:57]
	v_lshlrev_b32_e32 v2, 12, v2
	v_mov_b32_e32 v3, v57
	v_lshl_add_u64 v[28:29], v[0:1], 0, v[2:3]
	v_add_co_u32_e32 v4, vcc, s29, v28
	s_lshl_b32 s6, s14, 1
	s_nop 0
	v_addc_co_u32_e32 v5, vcc, 0, v29, vcc
	v_add_co_u32_e32 v8, vcc, s30, v28
	global_load_dwordx4 v[0:3], v[28:29], off nt
	s_nop 0
	global_load_dwordx4 v[4:7], v[4:5], off nt
	v_addc_co_u32_e32 v9, vcc, 0, v29, vcc
	v_add_co_u32_e32 v12, vcc, s31, v28
	v_lshl_add_u64 v[32:33], v[62:63], 0, s[6:7]
	s_nop 0
	v_addc_co_u32_e32 v13, vcc, 0, v29, vcc
	v_add_co_u32_e32 v16, vcc, s33, v28
	global_load_dwordx4 v[8:11], v[8:9], off nt
	s_nop 0
	global_load_dwordx4 v[12:15], v[12:13], off nt
	v_addc_co_u32_e32 v17, vcc, 0, v29, vcc
	v_add_co_u32_e32 v20, vcc, s34, v28
	s_nop 1
	v_addc_co_u32_e32 v21, vcc, 0, v29, vcc
	global_load_dwordx4 v[16:19], v[16:17], off nt
	s_nop 0
	global_load_dwordx4 v[20:23], v[20:21], off nt
	v_add_co_u32_e32 v24, vcc, s35, v28
	s_nop 1
	v_addc_co_u32_e32 v25, vcc, 0, v29, vcc
	global_load_dwordx4 v[24:27], v[24:25], off nt
	v_add_co_u32_e32 v28, vcc, s36, v28
	s_nop 1
	v_addc_co_u32_e32 v29, vcc, 0, v29, vcc
	global_load_dwordx4 v[28:31], v[28:29], off nt
	s_waitcnt vmcnt(7)
	ds_write2_b32 v82, v0, v1 offset1:1
	ds_write2_b32 v82, v2, v3 offset0:2 offset1:3
	s_waitcnt vmcnt(6)
	ds_write2_b32 v83, v4, v5 offset1:1
	ds_write2_b32 v84, v6, v7 offset1:1
	s_waitcnt vmcnt(5)
	ds_write2_b32 v85, v8, v9 offset1:1
	ds_write2_b32 v86, v10, v11 offset1:1
	s_waitcnt vmcnt(4)
	ds_write2_b32 v87, v12, v13 offset1:1
	ds_write2_b32 v88, v14, v15 offset1:1
	s_waitcnt vmcnt(3)
	ds_write2_b32 v89, v16, v17 offset1:1
	ds_write2_b32 v90, v18, v19 offset1:1
	s_waitcnt vmcnt(2)
	ds_write2_b32 v91, v20, v21 offset1:1
	ds_write2_b32 v92, v22, v23 offset1:1
	s_waitcnt vmcnt(1)
	ds_write2_b32 v93, v24, v25 offset1:1
	ds_write2_b32 v94, v26, v27 offset1:1
	s_waitcnt vmcnt(0)
	ds_write2_b32 v95, v28, v29 offset1:1
	ds_write2_b32 v96, v30, v31 offset1:1
	s_waitcnt lgkmcnt(0)
	ds_read2_b32 v[4:5], v81 offset0:33 offset1:41
	ds_read2_b32 v[6:7], v81 offset1:8
	ds_read2_b32 v[8:9], v81 offset0:66 offset1:74
	ds_read2_b32 v[10:11], v81 offset0:99 offset1:107
	ds_read2_b32 v[12:13], v81 offset0:132 offset1:140
	ds_read2_b32 v[14:15], v81 offset0:165 offset1:173
	ds_read2_b32 v[16:17], v81 offset0:198 offset1:206
	ds_read2_b32 v[18:19], v81 offset0:231 offset1:239
	s_waitcnt lgkmcnt(6)
	v_bfe_u32 v0, v6, 16, 1
	v_bfe_u32 v1, v4, 16, 1
	s_waitcnt lgkmcnt(5)
	v_bfe_u32 v2, v8, 16, 1
	s_waitcnt lgkmcnt(3)
	v_bfe_u32 v20, v12, 16, 1
	v_bfe_u32 v3, v10, 16, 1
	s_waitcnt lgkmcnt(2)
	v_bfe_u32 v21, v14, 16, 1
	v_add3_u32 v0, v6, v0, s37
	v_add3_u32 v1, v4, v1, s37
	v_add3_u32 v2, v8, v2, s37
	v_add3_u32 v4, v12, v20, s37
	s_waitcnt lgkmcnt(1)
	v_bfe_u32 v22, v16, 16, 1
	v_add3_u32 v3, v10, v3, s37
	v_add3_u32 v6, v14, v21, s37
	v_lshrrev_b32_e32 v0, 16, v0
	v_lshrrev_b32_e32 v2, 16, v2
	v_lshrrev_b32_e32 v4, 16, v4
	v_add3_u32 v8, v16, v22, s37
	v_and_or_b32 v0, v1, s38, v0
	v_and_or_b32 v1, v3, s38, v2
	v_and_or_b32 v2, v6, s38, v4
	s_waitcnt lgkmcnt(0)
	v_bfe_u32 v4, v18, 16, 1
	v_lshrrev_b32_e32 v3, 16, v8
	v_add3_u32 v4, v18, v4, s37
	v_and_or_b32 v3, v4, s38, v3
	v_or_b32_e32 v4, s0, v77
	v_lshlrev_b32_e32 v20, 10, v4
	v_mov_b32_e32 v21, v57
	v_lshl_add_u64 v[20:21], v[32:33], 0, v[20:21]
	global_store_dwordx4 v[20:21], v[0:3], off
	v_bfe_u32 v4, v19, 16, 1
	v_add3_u32 v4, v19, v4, s37
	v_bfe_u32 v0, v7, 16, 1
	v_add3_u32 v0, v7, v0, s37
	v_bfe_u32 v1, v5, 16, 1
	v_lshrrev_b32_e32 v0, 16, v0
	v_add3_u32 v1, v5, v1, s37
	v_and_or_b32 v0, v1, s38, v0
	v_bfe_u32 v1, v9, 16, 1
	v_add3_u32 v1, v9, v1, s37
	v_bfe_u32 v2, v11, 16, 1
	v_lshrrev_b32_e32 v1, 16, v1
	v_add3_u32 v2, v11, v2, s37
	v_and_or_b32 v1, v2, s38, v1
	v_bfe_u32 v2, v13, 16, 1
	v_add3_u32 v2, v13, v2, s37
	v_bfe_u32 v3, v15, 16, 1
	v_lshrrev_b32_e32 v2, 16, v2
	v_add3_u32 v3, v15, v3, s37
	v_and_or_b32 v2, v3, s38, v2
	v_bfe_u32 v3, v17, 16, 1
	v_add3_u32 v3, v17, v3, s37
	v_lshrrev_b32_e32 v3, 16, v3
	v_and_or_b32 v3, v4, s38, v3
	v_or_b32_e32 v4, s0, v78
	v_lshlrev_b32_e32 v4, 10, v4
	v_mov_b32_e32 v5, v57
	ds_read2_b32 v[6:7], v81 offset0:16 offset1:24
	v_lshl_add_u64 v[4:5], v[32:33], 0, v[4:5]
	global_store_dwordx4 v[4:5], v[0:3], off
	ds_read2_b32 v[4:5], v81 offset0:49 offset1:57
	ds_read2_b32 v[8:9], v81 offset0:82 offset1:90
	ds_read2_b32 v[10:11], v81 offset0:115 offset1:123
	s_waitcnt lgkmcnt(3)
	v_bfe_u32 v0, v6, 16, 1
	v_add3_u32 v0, v6, v0, s37
	s_waitcnt lgkmcnt(2)
	v_bfe_u32 v1, v4, 16, 1
	ds_read2_b32 v[12:13], v81 offset0:148 offset1:156
	v_lshrrev_b32_e32 v0, 16, v0
	v_add3_u32 v1, v4, v1, s37
	ds_read2_b32 v[14:15], v81 offset0:181 offset1:189
	v_and_or_b32 v0, v1, s38, v0
	s_waitcnt lgkmcnt(3)
	v_bfe_u32 v1, v8, 16, 1
	v_add3_u32 v1, v8, v1, s37
	s_waitcnt lgkmcnt(2)
	v_bfe_u32 v2, v10, 16, 1
	ds_read2_b32 v[16:17], v81 offset0:214 offset1:222
	v_lshrrev_b32_e32 v1, 16, v1
	v_add3_u32 v2, v10, v2, s37
	ds_read2_b32 v[18:19], v81 offset0:247 offset1:255
	v_and_or_b32 v1, v2, s38, v1
	s_waitcnt lgkmcnt(3)
	v_bfe_u32 v2, v12, 16, 1
	v_add3_u32 v2, v12, v2, s37
	s_waitcnt lgkmcnt(2)
	v_bfe_u32 v3, v14, 16, 1
	v_lshrrev_b32_e32 v2, 16, v2
	v_add3_u32 v3, v14, v3, s37
	v_and_or_b32 v2, v3, s38, v2
	s_waitcnt lgkmcnt(1)
	v_bfe_u32 v3, v16, 16, 1
	v_add3_u32 v3, v16, v3, s37
	s_waitcnt lgkmcnt(0)
	v_bfe_u32 v4, v18, 16, 1
	v_lshrrev_b32_e32 v3, 16, v3
	v_add3_u32 v4, v18, v4, s37
	v_and_or_b32 v3, v4, s38, v3
	v_or_b32_e32 v4, s0, v79
	v_lshlrev_b32_e32 v20, 10, v4
	v_mov_b32_e32 v21, v57
	v_lshl_add_u64 v[20:21], v[32:33], 0, v[20:21]
	global_store_dwordx4 v[20:21], v[0:3], off
	v_bfe_u32 v4, v19, 16, 1
	v_add3_u32 v4, v19, v4, s37
	v_bfe_u32 v0, v7, 16, 1
	v_add3_u32 v0, v7, v0, s37
	v_bfe_u32 v1, v5, 16, 1
	v_lshrrev_b32_e32 v0, 16, v0
	v_add3_u32 v1, v5, v1, s37
	v_and_or_b32 v0, v1, s38, v0
	v_bfe_u32 v1, v9, 16, 1
	v_add3_u32 v1, v9, v1, s37
	v_bfe_u32 v2, v11, 16, 1
	v_lshrrev_b32_e32 v1, 16, v1
	v_add3_u32 v2, v11, v2, s37
	v_and_or_b32 v1, v2, s38, v1
	v_bfe_u32 v2, v13, 16, 1
	v_add3_u32 v2, v13, v2, s37
	v_bfe_u32 v3, v15, 16, 1
	v_lshrrev_b32_e32 v2, 16, v2
	v_add3_u32 v3, v15, v3, s37
	v_and_or_b32 v2, v3, s38, v2
	v_bfe_u32 v3, v17, 16, 1
	v_add3_u32 v3, v17, v3, s37
	v_lshrrev_b32_e32 v3, 16, v3
	v_and_or_b32 v3, v4, s38, v3
	v_or_b32_e32 v4, s0, v80
	v_lshlrev_b32_e32 v4, 10, v4
	v_mov_b32_e32 v5, v57
	v_lshl_add_u64 v[4:5], v[32:33], 0, v[4:5]
	global_store_dwordx4 v[4:5], v[0:3], off
	s_waitcnt lgkmcnt(0)

; #define LAS __attribute__((address_space(3)))
; #define LDS_WAIT() asm volatile("s_waitcnt lgkmcnt(0)" ::: "memory")
; __device__ __forceinline__ unsigned pk2(float lo, float hi) { return f2bf(lo) | (f2bf(hi) << 16); }
; #define ARG_IN(i) argp(i)
; __device__ __forceinline__ void transpose_item(const float* __restrict__ W, int ldw, int k0, int c0, bf16* WT, int K, int drow0, LAS float* scr, int lane) {
;     { const int kr = lane >> 3, n4 = lane & 7;
;       f32x4 v[8];
; #pragma unroll
;       for (int i = 0; i < 8; ++i) v[i] = *(const f32x4*)(W + (size_t)(k0 + 8 * i + kr) * ldw + c0 + 4 * n4);
; #pragma unroll
;       for (int i = 0; i < 8; ++i) { LAS float* p = scr + (8 * i + kr) * 33 + 4 * n4; p[0] = v[i].x; p[1] = v[i].y; p[2] = v[i].z; p[3] = v[i].w; } }
;     LDS_WAIT(); asm volatile("" ::: "memory");
;     const int c = lane & 7;
; #pragma unroll
;     for (int j = 0; j < 4; ++j) { const int n = (lane >> 3) + 8 * j; const LAS float* s = scr + (8 * c) * 33 + n;
;         v4u o; o.x = pk2(s[0 * 33], s[1 * 33]); o.y = pk2(s[2 * 33], s[3 * 33]); o.z = pk2(s[4 * 33], s[5 * 33]); o.w = pk2(s[6 * 33], s[7 * 33]);
;         *(v4u*)(WT + (size_t)(drow0 + n) * K + k0 + 8 * c) = o; }
; __device__ __forceinline__ void weights_phase(int l, LAS unsigned char* lds, int vcu, int G, int wave, int lane) {
;     ...
;         } else if ((r -= IT_DN) < IT_IN) { const int kb = r / 208, nb = r % 208, L0 = 32 * nb, c0 = L0 < 3584 ? L0 : L0 + 8, pn = L0 >> 8, w = L0 & 255, hh = w >> 6, dh = (w >> 5) & 1;
;             transpose_item(ARG_IN(8) + (size_t)l * 1024 * DIN, DIN, 64 * kb, c0, WIN, 1024, 256 * pn + 128 * dh + 32 * hh, scr, lane);
.LBB0_110:
	s_andn2_b64 vcc, exec, s[12:13]
	s_cbranch_vccnz .LBB0_112
	s_add_i32 s0, s3, 0xdb00
	s_and_b32 s1, s0, 0xffff
	s_mulk_i32 s1, 0x4ec5
	s_lshr_b32 s6, s1, 16
	s_lshr_b32 s1, s1, 22
	s_mulk_i32 s1, 0xd0
	s_sub_i32 s0, s0, s1
	s_and_b32 s0, s0, 0xffff
	s_lshl_b32 s1, s0, 5
	s_or_b32 s12, s1, 8
	s_cmpk_lt_u32 s0, 0x70
	s_cselect_b32 s14, s1, s12
	s_lshl_b32 s15, s0, 7
	s_and_b32 s1, s1, 0x1f00
	s_and_b32 s15, s15, 0x80
	s_lshl_b32 s0, s0, 4
	s_or_b32 s1, s1, s15
	s_and_b32 s0, s0, 0x60
	s_load_dwordx2 s[12:13], s[96:97], 64
	s_waitcnt lgkmcnt(0)
	s_and_b32 s6, s6, 0x7fc0
	s_or_b32 s0, s1, s0
	s_lshl_b32 s1, s14, 2
	v_or_b32_e32 v2, s6, v77
	s_add_u32 s12, s12, s1
	s_addc_u32 s13, s13, 0
	v_mul_u32_u24_e32 v2, 0x1a08, v2
	v_lshl_add_u64 v[0:1], s[12:13], 0, v[56:57]
	v_lshlrev_b32_e32 v2, 2, v2
	v_mov_b32_e32 v3, v57
	v_lshl_add_u64 v[28:29], v[0:1], 0, v[2:3]
	v_add_co_u32_e32 v4, vcc, s39, v28
	s_lshl_b32 s6, s6, 1
	s_nop 0
	v_addc_co_u32_e32 v5, vcc, 0, v29, vcc
	v_add_co_u32_e32 v8, vcc, s40, v28
	global_load_dwordx4 v[0:3], v[28:29], off nt
	s_nop 0
	global_load_dwordx4 v[4:7], v[4:5], off offset:256 nt
	v_addc_co_u32_e32 v9, vcc, 0, v29, vcc
	v_add_co_u32_e32 v12, vcc, s41, v28
	v_lshl_add_u64 v[32:33], v[64:65], 0, s[6:7]
	s_nop 0
	v_addc_co_u32_e32 v13, vcc, 0, v29, vcc
	v_add_co_u32_e32 v16, vcc, s42, v28
	global_load_dwordx4 v[8:11], v[8:9], off offset:512 nt
	s_nop 0
	global_load_dwordx4 v[12:15], v[12:13], off offset:768 nt
	v_addc_co_u32_e32 v17, vcc, 0, v29, vcc
	v_add_co_u32_e32 v20, vcc, s43, v28
	s_nop 1
	v_addc_co_u32_e32 v21, vcc, 0, v29, vcc
	global_load_dwordx4 v[16:19], v[16:17], off offset:1024 nt
	s_nop 0
	global_load_dwordx4 v[20:23], v[20:21], off offset:1280 nt
	v_add_co_u32_e32 v24, vcc, s44, v28
	s_nop 1
	v_addc_co_u32_e32 v25, vcc, 0, v29, vcc
	global_load_dwordx4 v[24:27], v[24:25], off offset:1536 nt
	v_add_co_u32_e32 v28, vcc, s45, v28
	s_nop 1
	v_addc_co_u32_e32 v29, vcc, 0, v29, vcc
	global_load_dwordx4 v[28:31], v[28:29], off offset:1792 nt
	s_waitcnt vmcnt(7)
	ds_write2_b32 v82, v0, v1 offset1:1
	ds_write2_b32 v82, v2, v3 offset0:2 offset1:3
	s_waitcnt vmcnt(6)
	ds_write2_b32 v83, v4, v5 offset1:1
	ds_write2_b32 v84, v6, v7 offset1:1
	s_waitcnt vmcnt(5)
	ds_write2_b32 v85, v8, v9 offset1:1
	ds_write2_b32 v86, v10, v11 offset1:1
	s_waitcnt vmcnt(4)
	ds_write2_b32 v87, v12, v13 offset1:1
	ds_write2_b32 v88, v14, v15 offset1:1
	s_waitcnt vmcnt(3)
	ds_write2_b32 v89, v16, v17 offset1:1
	ds_write2_b32 v90, v18, v19 offset1:1
	s_waitcnt vmcnt(2)
	ds_write2_b32 v91, v20, v21 offset1:1
	ds_write2_b32 v92, v22, v23 offset1:1
	s_waitcnt vmcnt(1)
	ds_write2_b32 v93, v24, v25 offset1:1
	ds_write2_b32 v94, v26, v27 offset1:1
	s_waitcnt vmcnt(0)
	ds_write2_b32 v95, v28, v29 offset1:1
	ds_write2_b32 v96, v30, v31 offset1:1
	s_waitcnt lgkmcnt(0)
	ds_read2_b32 v[4:5], v81 offset0:33 offset1:41
	ds_read2_b32 v[6:7], v81 offset1:8
	ds_read2_b32 v[8:9], v81 offset0:66 offset1:74
	ds_read2_b32 v[10:11], v81 offset0:99 offset1:107
	ds_read2_b32 v[12:13], v81 offset0:132 offset1:140
	ds_read2_b32 v[14:15], v81 offset0:165 offset1:173
	ds_read2_b32 v[16:17], v81 offset0:198 offset1:206
	ds_read2_b32 v[18:19], v81 offset0:231 offset1:239
	s_waitcnt lgkmcnt(6)
	v_bfe_u32 v0, v6, 16, 1
	s_waitcnt lgkmcnt(5)
	v_bfe_u32 v2, v8, 16, 1
	v_bfe_u32 v1, v4, 16, 1
	s_waitcnt lgkmcnt(4)
	v_bfe_u32 v3, v10, 16, 1
	s_waitcnt lgkmcnt(3)
	v_bfe_u32 v20, v12, 16, 1
	v_add3_u32 v0, v6, v0, s37
	v_add3_u32 v2, v8, v2, s37
	s_waitcnt lgkmcnt(2)
	v_bfe_u32 v21, v14, 16, 1
	v_add3_u32 v1, v4, v1, s37
	v_add3_u32 v3, v10, v3, s37
	v_add3_u32 v4, v12, v20, s37
	v_lshrrev_b32_e32 v0, 16, v0
	v_lshrrev_b32_e32 v2, 16, v2
	v_add3_u32 v6, v14, v21, s37
	v_lshrrev_b32_e32 v4, 16, v4
	v_and_or_b32 v0, v1, s38, v0
	v_and_or_b32 v1, v3, s38, v2
	s_waitcnt lgkmcnt(1)
; #define LAS __attribute__((address_space(3)))
; __device__ __forceinline__ unsigned pk2(float lo, float hi) { return f2bf(lo) | (f2bf(hi) << 16); }
; __device__ __forceinline__ void transpose_item(const float* __restrict__ W, int ldw, int k0, int c0, bf16* WT, int K, int drow0, LAS float* scr, int lane) {
;     ...
;     const int c = lane & 7;
; #pragma unroll
;     for (int j = 0; j < 4; ++j) { const int n = (lane >> 3) + 8 * j; const LAS float* s = scr + (8 * c) * 33 + n;
;         v4u o; o.x = pk2(s[0 * 33], s[1 * 33]); o.y = pk2(s[2 * 33], s[3 * 33]); o.z = pk2(s[4 * 33], s[5 * 33]); o.w = pk2(s[6 * 33], s[7 * 33]);
;         *(v4u*)(WT + (size_t)(drow0 + n) * K + k0 + 8 * c) = o; }
	v_bfe_u32 v3, v16, 16, 1
	v_and_or_b32 v2, v6, s38, v4
	v_add3_u32 v3, v16, v3, s37
	s_waitcnt lgkmcnt(0)
	v_bfe_u32 v4, v18, 16, 1
	v_lshrrev_b32_e32 v3, 16, v3
	v_add3_u32 v4, v18, v4, s37
	v_and_or_b32 v3, v4, s38, v3
	v_or_b32_e32 v4, s0, v77
	v_lshlrev_b32_e32 v20, 11, v4
	v_mov_b32_e32 v21, v57
	v_lshl_add_u64 v[20:21], v[32:33], 0, v[20:21]
	global_store_dwordx4 v[20:21], v[0:3], off
	v_bfe_u32 v4, v19, 16, 1
	v_add3_u32 v4, v19, v4, s37
	v_bfe_u32 v0, v7, 16, 1
	v_add3_u32 v0, v7, v0, s37
	v_bfe_u32 v1, v5, 16, 1
	v_lshrrev_b32_e32 v0, 16, v0
	v_add3_u32 v1, v5, v1, s37
	v_and_or_b32 v0, v1, s38, v0
	v_bfe_u32 v1, v9, 16, 1
	v_add3_u32 v1, v9, v1, s37
	v_bfe_u32 v2, v11, 16, 1
	v_lshrrev_b32_e32 v1, 16, v1
	v_add3_u32 v2, v11, v2, s37
	v_and_or_b32 v1, v2, s38, v1
	v_bfe_u32 v2, v13, 16, 1
	v_add3_u32 v2, v13, v2, s37
	v_bfe_u32 v3, v15, 16, 1
	v_lshrrev_b32_e32 v2, 16, v2
	v_add3_u32 v3, v15, v3, s37
	v_and_or_b32 v2, v3, s38, v2
	v_bfe_u32 v3, v17, 16, 1
	v_add3_u32 v3, v17, v3, s37
	v_lshrrev_b32_e32 v3, 16, v3
	v_and_or_b32 v3, v4, s38, v3
	v_or_b32_e32 v4, s0, v78
	v_lshlrev_b32_e32 v4, 11, v4
	v_mov_b32_e32 v5, v57
	ds_read2_b32 v[6:7], v81 offset0:16 offset1:24
	v_lshl_add_u64 v[4:5], v[32:33], 0, v[4:5]
	global_store_dwordx4 v[4:5], v[0:3], off
	ds_read2_b32 v[4:5], v81 offset0:49 offset1:57
	ds_read2_b32 v[8:9], v81 offset0:82 offset1:90
	ds_read2_b32 v[10:11], v81 offset0:115 offset1:123
	s_waitcnt lgkmcnt(3)
	v_bfe_u32 v0, v6, 16, 1
	v_add3_u32 v0, v6, v0, s37
	s_waitcnt lgkmcnt(2)
	v_bfe_u32 v1, v4, 16, 1
	ds_read2_b32 v[12:13], v81 offset0:148 offset1:156
	v_lshrrev_b32_e32 v0, 16, v0
	v_add3_u32 v1, v4, v1, s37
	ds_read2_b32 v[14:15], v81 offset0:181 offset1:189
	v_and_or_b32 v0, v1, s38, v0
	s_waitcnt lgkmcnt(3)
	v_bfe_u32 v1, v8, 16, 1
	v_add3_u32 v1, v8, v1, s37
	s_waitcnt lgkmcnt(2)
	v_bfe_u32 v2, v10, 16, 1
	ds_read2_b32 v[16:17], v81 offset0:214 offset1:222
	v_lshrrev_b32_e32 v1, 16, v1
	v_add3_u32 v2, v10, v2, s37
	ds_read2_b32 v[18:19], v81 offset0:247 offset1:255
	v_and_or_b32 v1, v2, s38, v1
	s_waitcnt lgkmcnt(3)
	v_bfe_u32 v2, v12, 16, 1
	v_add3_u32 v2, v12, v2, s37
	s_waitcnt lgkmcnt(2)
	v_bfe_u32 v3, v14, 16, 1
	v_lshrrev_b32_e32 v2, 16, v2
	v_add3_u32 v3, v14, v3, s37
	v_and_or_b32 v2, v3, s38, v2
	s_waitcnt lgkmcnt(1)
	v_bfe_u32 v3, v16, 16, 1
	v_add3_u32 v3, v16, v3, s37
	s_waitcnt lgkmcnt(0)
	v_bfe_u32 v4, v18, 16, 1
	v_lshrrev_b32_e32 v3, 16, v3
	v_add3_u32 v4, v18, v4, s37
	v_and_or_b32 v3, v4, s38, v3
	v_or_b32_e32 v4, s0, v79
	v_lshlrev_b32_e32 v20, 11, v4
	v_mov_b32_e32 v21, v57
	v_lshl_add_u64 v[20:21], v[32:33], 0, v[20:21]
	global_store_dwordx4 v[20:21], v[0:3], off
	v_bfe_u32 v4, v19, 16, 1
	v_add3_u32 v4, v19, v4, s37
	v_bfe_u32 v0, v7, 16, 1
	v_add3_u32 v0, v7, v0, s37
	v_bfe_u32 v1, v5, 16, 1
	v_lshrrev_b32_e32 v0, 16, v0
	v_add3_u32 v1, v5, v1, s37
	v_and_or_b32 v0, v1, s38, v0
	v_bfe_u32 v1, v9, 16, 1
	v_add3_u32 v1, v9, v1, s37
	v_bfe_u32 v2, v11, 16, 1
	v_lshrrev_b32_e32 v1, 16, v1
	v_add3_u32 v2, v11, v2, s37
	v_and_or_b32 v1, v2, s38, v1
	v_bfe_u32 v2, v13, 16, 1
	v_add3_u32 v2, v13, v2, s37
	v_bfe_u32 v3, v15, 16, 1
	v_lshrrev_b32_e32 v2, 16, v2
	v_add3_u32 v3, v15, v3, s37
	v_and_or_b32 v2, v3, s38, v2
	v_bfe_u32 v3, v17, 16, 1
	v_add3_u32 v3, v17, v3, s37
	v_lshrrev_b32_e32 v3, 16, v3
	v_and_or_b32 v3, v4, s38, v3
	v_or_b32_e32 v4, s0, v80
	v_lshlrev_b32_e32 v4, 11, v4
	v_mov_b32_e32 v5, v57
	v_lshl_add_u64 v[4:5], v[32:33], 0, v[4:5]
	global_store_dwordx4 v[4:5], v[0:3], off
	s_waitcnt lgkmcnt(0)

; #define LAS __attribute__((address_space(3)))
; #define LDS_WAIT() asm volatile("s_waitcnt lgkmcnt(0)" ::: "memory")
; __device__ __forceinline__ unsigned pk2(float lo, float hi) { return f2bf(lo) | (f2bf(hi) << 16); }
; #define ARG_IN(i) argp(i)
; __device__ __forceinline__ void transpose_item(const float* __restrict__ W, int ldw, int k0, int c0, bf16* WT, int K, int drow0, LAS float* scr, int lane) {
;     { const int kr = lane >> 3, n4 = lane & 7;
;       f32x4 v[8];
; #pragma unroll
;       for (int i = 0; i < 8; ++i) v[i] = *(const f32x4*)(W + (size_t)(k0 + 8 * i + kr) * ldw + c0 + 4 * n4);
; #pragma unroll
;       for (int i = 0; i < 8; ++i) { LAS float* p = scr + (8 * i + kr) * 33 + 4 * n4; p[0] = v[i].x; p[1] = v[i].y; p[2] = v[i].z; p[3] = v[i].w; } }
;     LDS_WAIT(); asm volatile("" ::: "memory");
;     const int c = lane & 7;
; #pragma unroll
;     for (int j = 0; j < 4; ++j) { const int n = (lane >> 3) + 8 * j; const LAS float* s = scr + (8 * c) * 33 + n;
;         v4u o; o.x = pk2(s[0 * 33], s[1 * 33]); o.y = pk2(s[2 * 33], s[3 * 33]); o.z = pk2(s[4 * 33], s[5 * 33]); o.w = pk2(s[6 * 33], s[7 * 33]);
;         *(v4u*)(WT + (size_t)(drow0 + n) * K + k0 + 8 * c) = o; }
; __device__ __forceinline__ void weights_phase(int l, LAS unsigned char* lds, int vcu, int G, int wave, int lane) {
;     ...
;         } else if ((r -= IT_GU) < IT_DN) { const int j = r / 1408; r %= 1408; const int kb = r / 32, nb = r % 32;
;             transpose_item(ARG_IN(7) + (size_t)(l * 2 + j) * 2816 * 1024, 1024, 64 * kb, 32 * nb, WD + (size_t)j * 1024 * 2816, 2816, 32 * nb, scr, lane);
.LBB0_113:
	s_andn2_b64 vcc, exec, s[12:13]
	s_cbranch_vccnz .LBB0_115
	s_add_i32 s0, s3, 0xffffe600
	s_add_i32 s1, s3, 0xffffe080
	s_cmpk_lt_u32 s0, 0x580
	s_cselect_b32 s6, s0, s1
	s_cmpk_gt_u32 s0, 0x57f
	s_cselect_b32 s12, 0xb00000, 0
	s_load_dwordx2 s[0:1], s[96:97], 56
	s_waitcnt lgkmcnt(0)
	s_cselect_b32 s13, 0x580000, 0
	s_add_u32 s12, s0, s12
	s_addc_u32 s1, s1, 0
	s_lshl_b32 s0, s6, 1
	s_and_b32 s14, s0, 0xfc0
	s_lshl_b32 s0, s6, 5
	s_and_b32 s0, s0, 0x3e0
	s_add_u32 s6, s24, s13
	s_addc_u32 s15, s25, 0
	s_lshl_b32 s13, s0, 2
	s_add_u32 s12, s12, s13
	v_or_b32_e32 v2, s14, v77
	s_addc_u32 s13, s1, 0
	v_lshl_add_u64 v[0:1], s[12:13], 0, v[56:57]
	v_lshlrev_b32_e32 v2, 12, v2
	v_mov_b32_e32 v3, v57
	v_lshl_add_u64 v[28:29], v[0:1], 0, v[2:3]
	v_add_co_u32_e32 v4, vcc, s29, v28
	s_lshl_b32 s1, s14, 1
	s_nop 0
	v_addc_co_u32_e32 v5, vcc, 0, v29, vcc
	v_add_co_u32_e32 v8, vcc, s30, v28
	global_load_dwordx4 v[0:3], v[28:29], off nt
	s_nop 0
	global_load_dwordx4 v[4:7], v[4:5], off nt
	v_addc_co_u32_e32 v9, vcc, 0, v29, vcc
	v_add_co_u32_e32 v12, vcc, s31, v28
	s_add_u32 s12, s6, s1
	s_nop 0
	v_addc_co_u32_e32 v13, vcc, 0, v29, vcc
	v_add_co_u32_e32 v16, vcc, s33, v28
	global_load_dwordx4 v[8:11], v[8:9], off nt
	s_nop 0
	global_load_dwordx4 v[12:15], v[12:13], off nt
	v_addc_co_u32_e32 v17, vcc, 0, v29, vcc
	v_add_co_u32_e32 v20, vcc, s34, v28
	v_lshlrev_b32_e32 v32, 1, v58
	s_nop 0
	v_addc_co_u32_e32 v21, vcc, 0, v29, vcc
	global_load_dwordx4 v[16:19], v[16:17], off nt
	s_nop 0
	global_load_dwordx4 v[20:23], v[20:21], off nt
	v_add_co_u32_e32 v24, vcc, s35, v28
	v_mov_b32_e32 v33, v57
	s_nop 0
	v_addc_co_u32_e32 v25, vcc, 0, v29, vcc
	global_load_dwordx4 v[24:27], v[24:25], off nt
	v_add_co_u32_e32 v28, vcc, s36, v28
	s_addc_u32 s13, s15, 0
	s_nop 0
	v_addc_co_u32_e32 v29, vcc, 0, v29, vcc
	global_load_dwordx4 v[28:31], v[28:29], off nt
	v_lshl_add_u64 v[32:33], s[12:13], 0, v[32:33]
	s_waitcnt vmcnt(7)
	ds_write2_b32 v82, v0, v1 offset1:1
	ds_write2_b32 v82, v2, v3 offset0:2 offset1:3
	s_waitcnt vmcnt(6)
	ds_write2_b32 v83, v4, v5 offset1:1
	ds_write2_b32 v84, v6, v7 offset1:1
	s_waitcnt vmcnt(5)
	ds_write2_b32 v85, v8, v9 offset1:1
	ds_write2_b32 v86, v10, v11 offset1:1
	s_waitcnt vmcnt(4)
	ds_write2_b32 v87, v12, v13 offset1:1
	ds_write2_b32 v88, v14, v15 offset1:1
	s_waitcnt vmcnt(3)
	ds_write2_b32 v89, v16, v17 offset1:1
	ds_write2_b32 v90, v18, v19 offset1:1
	s_waitcnt vmcnt(2)
	ds_write2_b32 v91, v20, v21 offset1:1
	ds_write2_b32 v92, v22, v23 offset1:1
	s_waitcnt vmcnt(1)
	ds_write2_b32 v93, v24, v25 offset1:1
	ds_write2_b32 v94, v26, v27 offset1:1
	s_waitcnt vmcnt(0)
	ds_write2_b32 v95, v28, v29 offset1:1
	ds_write2_b32 v96, v30, v31 offset1:1
	s_waitcnt lgkmcnt(0)
	ds_read2_b32 v[4:5], v81 offset0:33 offset1:41
	ds_read2_b32 v[6:7], v81 offset1:8
	ds_read2_b32 v[8:9], v81 offset0:66 offset1:74
	ds_read2_b32 v[10:11], v81 offset0:99 offset1:107
	ds_read2_b32 v[12:13], v81 offset0:132 offset1:140
	ds_read2_b32 v[14:15], v81 offset0:165 offset1:173
	ds_read2_b32 v[16:17], v81 offset0:198 offset1:206
	s_waitcnt lgkmcnt(6)
	v_bfe_u32 v1, v4, 16, 1
	s_waitcnt lgkmcnt(5)
	v_bfe_u32 v0, v6, 16, 1
	s_waitcnt lgkmcnt(2)
	v_bfe_u32 v18, v12, 16, 1
	v_bfe_u32 v2, v8, 16, 1
	v_add3_u32 v1, v4, v1, s37
	v_add3_u32 v4, v12, v18, s37
	ds_read2_b32 v[18:19], v81 offset0:231 offset1:239
	v_bfe_u32 v3, v10, 16, 1
	v_add3_u32 v0, v6, v0, s37
	v_add3_u32 v2, v8, v2, s37
	v_add3_u32 v3, v10, v3, s37
	v_lshrrev_b32_e32 v0, 16, v0
	v_lshrrev_b32_e32 v2, 16, v2
	v_and_or_b32 v0, v1, s38, v0
	v_and_or_b32 v1, v3, s38, v2
	s_waitcnt lgkmcnt(2)
	v_bfe_u32 v2, v14, 16, 1
	v_lshrrev_b32_e32 v4, 16, v4
	v_add3_u32 v2, v14, v2, s37
	s_waitcnt lgkmcnt(1)
; #define LAS __attribute__((address_space(3)))
; __device__ __forceinline__ unsigned pk2(float lo, float hi) { return f2bf(lo) | (f2bf(hi) << 16); }
; __device__ __forceinline__ void transpose_item(const float* __restrict__ W, int ldw, int k0, int c0, bf16* WT, int K, int drow0, LAS float* scr, int lane) {
;     ...
;     const int c = lane & 7;
; #pragma unroll
;     for (int j = 0; j < 4; ++j) { const int n = (lane >> 3) + 8 * j; const LAS float* s = scr + (8 * c) * 33 + n;
;         v4u o; o.x = pk2(s[0 * 33], s[1 * 33]); o.y = pk2(s[2 * 33], s[3 * 33]); o.z = pk2(s[4 * 33], s[5 * 33]); o.w = pk2(s[6 * 33], s[7 * 33]);
;         *(v4u*)(WT + (size_t)(drow0 + n) * K + k0 + 8 * c) = o; }
	v_bfe_u32 v3, v16, 16, 1
	v_and_or_b32 v2, v2, s38, v4
	v_add3_u32 v3, v16, v3, s37
	s_waitcnt lgkmcnt(0)
	v_bfe_u32 v4, v18, 16, 1
	v_lshrrev_b32_e32 v3, 16, v3
	v_add3_u32 v4, v18, v4, s37
	v_and_or_b32 v3, v4, s38, v3
	v_or_b32_e32 v4, s0, v77
	v_mul_u32_u24_e32 v4, 0xb00, v4
	v_lshlrev_b32_e32 v20, 1, v4
	v_mov_b32_e32 v21, v57
	v_lshl_add_u64 v[20:21], v[32:33], 0, v[20:21]
	global_store_dwordx4 v[20:21], v[0:3], off
	v_bfe_u32 v4, v19, 16, 1
	v_add3_u32 v4, v19, v4, s37
	v_bfe_u32 v0, v7, 16, 1
	v_add3_u32 v0, v7, v0, s37
	v_bfe_u32 v1, v5, 16, 1
	v_lshrrev_b32_e32 v0, 16, v0
	v_add3_u32 v1, v5, v1, s37
	v_and_or_b32 v0, v1, s38, v0
	v_bfe_u32 v1, v9, 16, 1
	v_add3_u32 v1, v9, v1, s37
	v_bfe_u32 v2, v11, 16, 1
	v_lshrrev_b32_e32 v1, 16, v1
	v_add3_u32 v2, v11, v2, s37
	v_and_or_b32 v1, v2, s38, v1
	v_bfe_u32 v2, v13, 16, 1
	v_add3_u32 v2, v13, v2, s37
	v_bfe_u32 v3, v15, 16, 1
	v_lshrrev_b32_e32 v2, 16, v2
	v_add3_u32 v3, v15, v3, s37
	v_and_or_b32 v2, v3, s38, v2
	v_bfe_u32 v3, v17, 16, 1
	v_add3_u32 v3, v17, v3, s37
	v_lshrrev_b32_e32 v3, 16, v3
	v_and_or_b32 v3, v4, s38, v3
	v_or_b32_e32 v4, s0, v78
	v_mul_u32_u24_e32 v4, 0xb00, v4
	v_lshlrev_b32_e32 v4, 1, v4
	v_mov_b32_e32 v5, v57
	ds_read2_b32 v[6:7], v81 offset0:16 offset1:24
	v_lshl_add_u64 v[4:5], v[32:33], 0, v[4:5]
	global_store_dwordx4 v[4:5], v[0:3], off
	ds_read2_b32 v[4:5], v81 offset0:49 offset1:57
	ds_read2_b32 v[8:9], v81 offset0:82 offset1:90
	ds_read2_b32 v[10:11], v81 offset0:115 offset1:123
	s_waitcnt lgkmcnt(3)
	v_bfe_u32 v0, v6, 16, 1
	v_add3_u32 v0, v6, v0, s37
	s_waitcnt lgkmcnt(2)
	v_bfe_u32 v1, v4, 16, 1
	ds_read2_b32 v[12:13], v81 offset0:148 offset1:156
	v_lshrrev_b32_e32 v0, 16, v0
	v_add3_u32 v1, v4, v1, s37
	ds_read2_b32 v[14:15], v81 offset0:181 offset1:189
	v_and_or_b32 v0, v1, s38, v0
	s_waitcnt lgkmcnt(3)
	v_bfe_u32 v1, v8, 16, 1
	v_add3_u32 v1, v8, v1, s37
	s_waitcnt lgkmcnt(2)
	v_bfe_u32 v2, v10, 16, 1
	ds_read2_b32 v[16:17], v81 offset0:214 offset1:222
	v_lshrrev_b32_e32 v1, 16, v1
	v_add3_u32 v2, v10, v2, s37
	ds_read2_b32 v[18:19], v81 offset0:247 offset1:255
	v_and_or_b32 v1, v2, s38, v1
	s_waitcnt lgkmcnt(3)
	v_bfe_u32 v2, v12, 16, 1
	v_add3_u32 v2, v12, v2, s37
	s_waitcnt lgkmcnt(2)
	v_bfe_u32 v3, v14, 16, 1
	v_lshrrev_b32_e32 v2, 16, v2
	v_add3_u32 v3, v14, v3, s37
	v_and_or_b32 v2, v3, s38, v2
	s_waitcnt lgkmcnt(1)
	v_bfe_u32 v3, v16, 16, 1
	v_add3_u32 v3, v16, v3, s37
	s_waitcnt lgkmcnt(0)
	v_bfe_u32 v4, v18, 16, 1
	v_lshrrev_b32_e32 v3, 16, v3
	v_add3_u32 v4, v18, v4, s37
	v_and_or_b32 v3, v4, s38, v3
	v_or_b32_e32 v4, s0, v79
	v_mul_u32_u24_e32 v4, 0xb00, v4
	v_lshlrev_b32_e32 v20, 1, v4
	v_mov_b32_e32 v21, v57
	v_lshl_add_u64 v[20:21], v[32:33], 0, v[20:21]
	global_store_dwordx4 v[20:21], v[0:3], off
	v_bfe_u32 v4, v19, 16, 1
	v_add3_u32 v4, v19, v4, s37
	v_bfe_u32 v0, v7, 16, 1
	v_add3_u32 v0, v7, v0, s37
	v_bfe_u32 v1, v5, 16, 1
	v_lshrrev_b32_e32 v0, 16, v0
	v_add3_u32 v1, v5, v1, s37
	v_and_or_b32 v0, v1, s38, v0
	v_bfe_u32 v1, v9, 16, 1
	v_add3_u32 v1, v9, v1, s37
	v_bfe_u32 v2, v11, 16, 1
	v_lshrrev_b32_e32 v1, 16, v1
	v_add3_u32 v2, v11, v2, s37
	v_and_or_b32 v1, v2, s38, v1
	v_bfe_u32 v2, v13, 16, 1
	v_add3_u32 v2, v13, v2, s37
	v_bfe_u32 v3, v15, 16, 1
	v_lshrrev_b32_e32 v2, 16, v2
	v_add3_u32 v3, v15, v3, s37
	v_and_or_b32 v2, v3, s38, v2
	v_bfe_u32 v3, v17, 16, 1
	v_add3_u32 v3, v17, v3, s37
	v_lshrrev_b32_e32 v3, 16, v3
	v_and_or_b32 v3, v4, s38, v3
	v_or_b32_e32 v4, s0, v80
	v_mul_u32_u24_e32 v4, 0xb00, v4
	v_lshlrev_b32_e32 v4, 1, v4
	v_mov_b32_e32 v5, v57
	v_lshl_add_u64 v[4:5], v[32:33], 0, v[4:5]
	global_store_dwordx4 v[4:5], v[0:3], off
	s_waitcnt lgkmcnt(0)

; #define LAS __attribute__((address_space(3)))
; #define LDS_WAIT() asm volatile("s_waitcnt lgkmcnt(0)" ::: "memory")
; __device__ __forceinline__ unsigned pk2(float lo, float hi) { return f2bf(lo) | (f2bf(hi) << 16); }
; #define ARG_IN(i) argp(i)
; __device__ __forceinline__ void transpose_item(const float* __restrict__ W, int ldw, int k0, int c0, bf16* WT, int K, int drow0, LAS float* scr, int lane) {
;     { const int kr = lane >> 3, n4 = lane & 7;
;       f32x4 v[8];
; #pragma unroll
;       for (int i = 0; i < 8; ++i) v[i] = *(const f32x4*)(W + (size_t)(k0 + 8 * i + kr) * ldw + c0 + 4 * n4);
; #pragma unroll
;       for (int i = 0; i < 8; ++i) { LAS float* p = scr + (8 * i + kr) * 33 + 4 * n4; p[0] = v[i].x; p[1] = v[i].y; p[2] = v[i].z; p[3] = v[i].w; } }
;     LDS_WAIT(); asm volatile("" ::: "memory");
;     const int c = lane & 7;
; #pragma unroll
;     for (int j = 0; j < 4; ++j) { const int n = (lane >> 3) + 8 * j; const LAS float* s = scr + (8 * c) * 33 + n;
;         v4u o; o.x = pk2(s[0 * 33], s[1 * 33]); o.y = pk2(s[2 * 33], s[3 * 33]); o.z = pk2(s[4 * 33], s[5 * 33]); o.w = pk2(s[6 * 33], s[7 * 33]);
;         *(v4u*)(WT + (size_t)(drow0 + n) * K + k0 + 8 * c) = o; }
; __device__ __forceinline__ void weights_phase(int l, LAS unsigned char* lds, int vcu, int G, int wave, int lane) {
;     ...
;         } else if ((r -= IT_EFF) < IT_GU) { const int j = r / 2816; r %= 2816; const int isup = r / 1408; r %= 1408; const int kb = r / 88, nb = r % 88, f0 = 32 * nb;
;             const float* src = (isup ? ARG_IN(6) : ARG_IN(5)) + (size_t)(l * 2 + j) * 1024 * 2816;
;             transpose_item(src, 2816, 64 * kb, f0, WGU + (size_t)j * NGU * 1024, 1024, 256 * (f0 >> 7) + 128 * isup + (f0 & 127), scr, lane);
.LBB0_121:
	s_mul_hi_u32 s6, s1, 0xba2e8ba3
	s_lshr_b32 s6, s6, 10
	s_mul_i32 s14, s6, 0x580
	s_sub_i32 s1, s1, s14
	s_mul_i32 s14, s1, 0xba2f
	s_lshr_b32 s15, s14, 16
	s_lshr_b32 s14, s14, 22
	s_mulk_i32 s14, 0x58
	s_sub_i32 s1, s1, s14
	s_and_b32 s1, s1, 0xffff
	s_lshl_b32 s14, s1, 5
	s_cmpk_gt_u32 s0, 0xaff
	s_cselect_b32 s0, 0xb00000, 0
	s_add_u32 s12, s12, s0
	s_addc_u32 s13, s13, 0
	s_and_b32 s15, s15, 0xffc0
	s_add_u32 s16, s22, s0
	s_addc_u32 s17, s23, 0
	s_lshl_b32 s0, s1, 6
	s_and_b32 s0, s0, 0x1f00
	s_lshl_b32 s6, s6, 7
	s_add_i32 s0, s0, s6
	s_and_b32 s6, s14, 0x60
	s_or_b32 s0, s0, s6
	s_lshl_b32 s1, s1, 7
	v_or_b32_e32 v2, s15, v77
	s_add_u32 s12, s12, s1
	s_addc_u32 s13, s13, 0
	v_mul_u32_u24_e32 v2, 0xb00, v2
	v_lshl_add_u64 v[0:1], s[12:13], 0, v[56:57]
	v_lshlrev_b32_e32 v2, 2, v2
	v_mov_b32_e32 v3, v57
	v_lshl_add_u64 v[28:29], v[0:1], 0, v[2:3]
	v_add_co_u32_e32 v4, vcc, s46, v28
	s_lshl_b32 s1, s15, 1
	s_nop 0
	v_addc_co_u32_e32 v5, vcc, 0, v29, vcc
	v_add_co_u32_e32 v8, vcc, s47, v28
	global_load_dwordx4 v[0:3], v[28:29], off nt
	s_nop 0
	global_load_dwordx4 v[4:7], v[4:5], off nt
	v_addc_co_u32_e32 v9, vcc, 0, v29, vcc
	v_add_co_u32_e32 v12, vcc, s48, v28
	s_add_u32 s12, s16, s1
	s_nop 0
	v_addc_co_u32_e32 v13, vcc, 0, v29, vcc
	v_add_co_u32_e32 v16, vcc, s49, v28
	global_load_dwordx4 v[8:11], v[8:9], off nt
	s_nop 0
	global_load_dwordx4 v[12:15], v[12:13], off nt
	v_addc_co_u32_e32 v17, vcc, 0, v29, vcc
	v_add_co_u32_e32 v20, vcc, s50, v28
	v_lshlrev_b32_e32 v32, 1, v58
	s_nop 0
	v_addc_co_u32_e32 v21, vcc, 0, v29, vcc
	global_load_dwordx4 v[16:19], v[16:17], off nt
	s_nop 0
	global_load_dwordx4 v[20:23], v[20:21], off nt
	v_add_co_u32_e32 v24, vcc, s51, v28
	v_mov_b32_e32 v33, v57
	s_nop 0
	v_addc_co_u32_e32 v25, vcc, 0, v29, vcc
	global_load_dwordx4 v[24:27], v[24:25], off nt
	v_add_co_u32_e32 v28, vcc, s52, v28
	s_addc_u32 s13, s17, 0
	s_nop 0
	v_addc_co_u32_e32 v29, vcc, 0, v29, vcc
	global_load_dwordx4 v[28:31], v[28:29], off nt
	v_lshl_add_u64 v[32:33], s[12:13], 0, v[32:33]
	s_waitcnt vmcnt(7)
	ds_write2_b32 v82, v0, v1 offset1:1
	ds_write2_b32 v82, v2, v3 offset0:2 offset1:3
	s_waitcnt vmcnt(6)
	ds_write2_b32 v83, v4, v5 offset1:1
	ds_write2_b32 v84, v6, v7 offset1:1
	s_waitcnt vmcnt(5)
	ds_write2_b32 v85, v8, v9 offset1:1
	ds_write2_b32 v86, v10, v11 offset1:1
	s_waitcnt vmcnt(4)
	ds_write2_b32 v87, v12, v13 offset1:1
	ds_write2_b32 v88, v14, v15 offset1:1
	s_waitcnt vmcnt(3)
	ds_write2_b32 v89, v16, v17 offset1:1
	ds_write2_b32 v90, v18, v19 offset1:1
	s_waitcnt vmcnt(2)
	ds_write2_b32 v91, v20, v21 offset1:1
	ds_write2_b32 v92, v22, v23 offset1:1
	s_waitcnt vmcnt(1)
	ds_write2_b32 v93, v24, v25 offset1:1
	ds_write2_b32 v94, v26, v27 offset1:1
	s_waitcnt vmcnt(0)
	ds_write2_b32 v95, v28, v29 offset1:1
	ds_write2_b32 v96, v30, v31 offset1:1
	s_waitcnt lgkmcnt(0)
	ds_read2_b32 v[4:5], v81 offset0:33 offset1:41
	ds_read2_b32 v[6:7], v81 offset1:8
	ds_read2_b32 v[8:9], v81 offset0:66 offset1:74
	ds_read2_b32 v[10:11], v81 offset0:99 offset1:107
	ds_read2_b32 v[12:13], v81 offset0:132 offset1:140
	ds_read2_b32 v[14:15], v81 offset0:165 offset1:173
	ds_read2_b32 v[16:17], v81 offset0:198 offset1:206
	s_waitcnt lgkmcnt(5)
	v_bfe_u32 v0, v6, 16, 1
	s_waitcnt lgkmcnt(4)
	v_bfe_u32 v2, v8, 16, 1
	v_bfe_u32 v1, v4, 16, 1
	s_waitcnt lgkmcnt(3)
	v_bfe_u32 v3, v10, 16, 1
	v_add3_u32 v0, v6, v0, s37
	v_add3_u32 v2, v8, v2, s37
	s_waitcnt lgkmcnt(2)
	v_bfe_u32 v18, v12, 16, 1
	s_waitcnt lgkmcnt(1)
	v_bfe_u32 v19, v14, 16, 1
	v_add3_u32 v1, v4, v1, s37
	v_add3_u32 v3, v10, v3, s37
	v_lshrrev_b32_e32 v0, 16, v0
	v_lshrrev_b32_e32 v2, 16, v2
	v_add3_u32 v4, v12, v18, s37
	v_and_or_b32 v0, v1, s38, v0
	v_and_or_b32 v1, v3, s38, v2
	v_add3_u32 v2, v14, v19, s37
	ds_read2_b32 v[18:19], v81 offset0:231 offset1:239
	v_lshrrev_b32_e32 v4, 16, v4
	s_waitcnt lgkmcnt(1)
; #define LAS __attribute__((address_space(3)))
; #define LDS_WAIT() asm volatile("s_waitcnt lgkmcnt(0)" ::: "memory")
; __device__ __forceinline__ unsigned pk2(float lo, float hi) { return f2bf(lo) | (f2bf(hi) << 16); }
; __device__ __forceinline__ void transpose_item(const float* __restrict__ W, int ldw, int k0, int c0, bf16* WT, int K, int drow0, LAS float* scr, int lane) {
;     ...
;     const int c = lane & 7;
; #pragma unroll
;     for (int j = 0; j < 4; ++j) { const int n = (lane >> 3) + 8 * j; const LAS float* s = scr + (8 * c) * 33 + n;
;         v4u o; o.x = pk2(s[0 * 33], s[1 * 33]); o.y = pk2(s[2 * 33], s[3 * 33]); o.z = pk2(s[4 * 33], s[5 * 33]); o.w = pk2(s[6 * 33], s[7 * 33]);
;         *(v4u*)(WT + (size_t)(drow0 + n) * K + k0 + 8 * c) = o; }
;     LDS_WAIT(); asm volatile("" ::: "memory");
	v_bfe_u32 v3, v16, 16, 1
	v_and_or_b32 v2, v2, s38, v4
	v_add3_u32 v3, v16, v3, s37
	s_waitcnt lgkmcnt(0)
	v_bfe_u32 v4, v18, 16, 1
	v_lshrrev_b32_e32 v3, 16, v3
	v_add3_u32 v4, v18, v4, s37
	v_and_or_b32 v3, v4, s38, v3
	v_or_b32_e32 v4, s0, v77
	v_lshlrev_b32_e32 v20, 11, v4
	v_mov_b32_e32 v21, v57
	v_lshl_add_u64 v[20:21], v[32:33], 0, v[20:21]
	global_store_dwordx4 v[20:21], v[0:3], off
	v_bfe_u32 v4, v19, 16, 1
	v_add3_u32 v4, v19, v4, s37
	v_bfe_u32 v0, v7, 16, 1
	v_add3_u32 v0, v7, v0, s37
	v_bfe_u32 v1, v5, 16, 1
	v_lshrrev_b32_e32 v0, 16, v0
	v_add3_u32 v1, v5, v1, s37
	v_and_or_b32 v0, v1, s38, v0
	v_bfe_u32 v1, v9, 16, 1
	v_add3_u32 v1, v9, v1, s37
	v_bfe_u32 v2, v11, 16, 1
	v_lshrrev_b32_e32 v1, 16, v1
	v_add3_u32 v2, v11, v2, s37
	v_and_or_b32 v1, v2, s38, v1
	v_bfe_u32 v2, v13, 16, 1
	v_add3_u32 v2, v13, v2, s37
	v_bfe_u32 v3, v15, 16, 1
	v_lshrrev_b32_e32 v2, 16, v2
	v_add3_u32 v3, v15, v3, s37
	v_and_or_b32 v2, v3, s38, v2
	v_bfe_u32 v3, v17, 16, 1
	v_add3_u32 v3, v17, v3, s37
	v_lshrrev_b32_e32 v3, 16, v3
	v_and_or_b32 v3, v4, s38, v3
	v_or_b32_e32 v4, s0, v78
	v_lshlrev_b32_e32 v4, 11, v4
	v_mov_b32_e32 v5, v57
	ds_read2_b32 v[6:7], v81 offset0:16 offset1:24
	v_lshl_add_u64 v[4:5], v[32:33], 0, v[4:5]
	global_store_dwordx4 v[4:5], v[0:3], off
	ds_read2_b32 v[4:5], v81 offset0:49 offset1:57
	ds_read2_b32 v[8:9], v81 offset0:82 offset1:90
	ds_read2_b32 v[10:11], v81 offset0:115 offset1:123
	s_waitcnt lgkmcnt(3)
	v_bfe_u32 v0, v6, 16, 1
	v_add3_u32 v0, v6, v0, s37
	s_waitcnt lgkmcnt(2)
	v_bfe_u32 v1, v4, 16, 1
	ds_read2_b32 v[12:13], v81 offset0:148 offset1:156
	v_lshrrev_b32_e32 v0, 16, v0
	v_add3_u32 v1, v4, v1, s37
	ds_read2_b32 v[14:15], v81 offset0:181 offset1:189
	v_and_or_b32 v0, v1, s38, v0
	s_waitcnt lgkmcnt(3)
	v_bfe_u32 v1, v8, 16, 1
	v_add3_u32 v1, v8, v1, s37
	s_waitcnt lgkmcnt(2)
	v_bfe_u32 v2, v10, 16, 1
	ds_read2_b32 v[16:17], v81 offset0:214 offset1:222
	v_lshrrev_b32_e32 v1, 16, v1
	v_add3_u32 v2, v10, v2, s37
	ds_read2_b32 v[18:19], v81 offset0:247 offset1:255
	v_and_or_b32 v1, v2, s38, v1
	s_waitcnt lgkmcnt(3)
	v_bfe_u32 v2, v12, 16, 1
	v_add3_u32 v2, v12, v2, s37
	s_waitcnt lgkmcnt(2)
	v_bfe_u32 v3, v14, 16, 1
	v_lshrrev_b32_e32 v2, 16, v2
	v_add3_u32 v3, v14, v3, s37
	v_and_or_b32 v2, v3, s38, v2
	s_waitcnt lgkmcnt(1)
	v_bfe_u32 v3, v16, 16, 1
	v_add3_u32 v3, v16, v3, s37
	s_waitcnt lgkmcnt(0)
	v_bfe_u32 v4, v18, 16, 1
	v_lshrrev_b32_e32 v3, 16, v3
	v_add3_u32 v4, v18, v4, s37
	v_and_or_b32 v3, v4, s38, v3
	v_or_b32_e32 v4, s0, v79
	v_lshlrev_b32_e32 v20, 11, v4
	v_mov_b32_e32 v21, v57
	v_lshl_add_u64 v[20:21], v[32:33], 0, v[20:21]
	global_store_dwordx4 v[20:21], v[0:3], off
	v_bfe_u32 v4, v19, 16, 1
	v_add3_u32 v4, v19, v4, s37
	v_bfe_u32 v0, v7, 16, 1
	v_add3_u32 v0, v7, v0, s37
	v_bfe_u32 v1, v5, 16, 1
	v_lshrrev_b32_e32 v0, 16, v0
	v_add3_u32 v1, v5, v1, s37
	v_and_or_b32 v0, v1, s38, v0
	v_bfe_u32 v1, v9, 16, 1
	v_add3_u32 v1, v9, v1, s37
	v_bfe_u32 v2, v11, 16, 1
	v_lshrrev_b32_e32 v1, 16, v1
	v_add3_u32 v2, v11, v2, s37
	v_and_or_b32 v1, v2, s38, v1
	v_bfe_u32 v2, v13, 16, 1
	v_add3_u32 v2, v13, v2, s37
	v_bfe_u32 v3, v15, 16, 1
	v_lshrrev_b32_e32 v2, 16, v2
	v_add3_u32 v3, v15, v3, s37
	v_and_or_b32 v2, v3, s38, v2
	v_bfe_u32 v3, v17, 16, 1
	v_add3_u32 v3, v17, v3, s37
	v_lshrrev_b32_e32 v3, 16, v3
	v_and_or_b32 v3, v4, s38, v3
	v_or_b32_e32 v4, s0, v80
	v_lshlrev_b32_e32 v4, 11, v4
	v_mov_b32_e32 v5, v57
	v_lshl_add_u64 v[4:5], v[32:33], 0, v[4:5]
	global_store_dwordx4 v[4:5], v[0:3], off
	s_waitcnt lgkmcnt(0)

; #define LAS __attribute__((address_space(3)))
; #define LDS_WAIT() asm volatile("s_waitcnt lgkmcnt(0)" ::: "memory")
; __device__ __forceinline__ unsigned pk2(float lo, float hi) { return f2bf(lo) | (f2bf(hi) << 16); }
; #define ARG_IN(i) argp(i)
; __device__ __forceinline__ void transpose_item(const float* __restrict__ W, int ldw, int k0, int c0, bf16* WT, int K, int drow0, LAS float* scr, int lane) {
;     { const int kr = lane >> 3, n4 = lane & 7;
;       f32x4 v[8];
; #pragma unroll
;       for (int i = 0; i < 8; ++i) v[i] = *(const f32x4*)(W + (size_t)(k0 + 8 * i + kr) * ldw + c0 + 4 * n4);
; #pragma unroll
;       for (int i = 0; i < 8; ++i) { LAS float* p = scr + (8 * i + kr) * 33 + 4 * n4; p[0] = v[i].x; p[1] = v[i].y; p[2] = v[i].z; p[3] = v[i].w; } }
;     LDS_WAIT(); asm volatile("" ::: "memory");
;     const int c = lane & 7;
; #pragma unroll
;     for (int j = 0; j < 4; ++j) { const int n = (lane >> 3) + 8 * j; const LAS float* s = scr + (8 * c) * 33 + n;
;         v4u o; o.x = pk2(s[0 * 33], s[1 * 33]); o.y = pk2(s[2 * 33], s[3 * 33]); o.z = pk2(s[4 * 33], s[5 * 33]); o.w = pk2(s[6 * 33], s[7 * 33]);
;         *(v4u*)(WT + (size_t)(drow0 + n) * K + k0 + 8 * c) = o; }
; __device__ __forceinline__ void weights_phase(int l, LAS unsigned char* lds, int vcu, int G, int wave, int lane) {
;     ...
;         } else if ((r -= IT_BR) < IT_WO) { const int kb = r / 32, nb = r % 32; transpose_item(ARG_IN(15) + (size_t)l * 1024 * 1024, 1024, 64 * kb, 32 * nb, WO, 1024, 32 * nb, scr, lane);
.LBB0_192:
	s_andn2_b64 vcc, exec, s[10:11]
	s_cbranch_vccnz .LBB0_194
	s_lshl_b32 s0, s3, 1
	s_and_b32 s0, s0, 0x7fc0
	s_add_i32 s94, s0, 0xffff9800
	s_lshl_b32 s0, s3, 5
	s_and_b32 s0, s0, 0x3e0
	s_load_dwordx2 s[10:11], s[96:97], 0x78
	s_waitcnt lgkmcnt(0)
	s_lshl_b32 s1, s0, 2
	s_add_u32 s10, s10, s1
	v_or_b32_e32 v4, s94, v29
	s_addc_u32 s11, s11, 0
	v_lshlrev_b32_e32 v0, 2, v26
	v_lshl_add_u64 v[2:3], s[10:11], 0, v[0:1]
	v_lshlrev_b32_e32 v0, 10, v4
	v_lshl_add_u64 v[40:41], v[0:1], 2, v[2:3]
	s_mov_b32 s1, 0x400000
	v_add_co_u32_e32 v2, vcc, s1, v40
	s_mov_b32 s1, 0x408000
	s_nop 0
	v_addc_co_u32_e32 v3, vcc, 0, v41, vcc
	v_add_co_u32_e32 v6, vcc, s1, v40
	s_mov_b32 s1, 0x410000
	s_nop 0
	v_addc_co_u32_e32 v7, vcc, 0, v41, vcc
	v_add_co_u32_e32 v10, vcc, s1, v40
	s_mov_b32 s1, 0x418000
	s_nop 0
	v_addc_co_u32_e32 v11, vcc, 0, v41, vcc
	v_add_co_u32_e32 v14, vcc, s1, v40
	s_mov_b32 s1, 0x420000
	s_nop 0
	v_addc_co_u32_e32 v15, vcc, 0, v41, vcc
	v_add_co_u32_e32 v18, vcc, s1, v40
	s_mov_b32 s1, 0x428000
	s_nop 0
	v_addc_co_u32_e32 v19, vcc, 0, v41, vcc
	v_add_co_u32_e32 v22, vcc, s1, v40
	global_load_dwordx4 v[2:5], v[2:3], off nt
	s_nop 0
	global_load_dwordx4 v[6:9], v[6:7], off nt
	v_addc_co_u32_e32 v23, vcc, 0, v41, vcc
	global_load_dwordx4 v[10:13], v[10:11], off nt
	s_nop 0
	global_load_dwordx4 v[14:17], v[14:15], off nt
	s_nop 0
	global_load_dwordx4 v[18:21], v[18:19], off nt
	s_nop 0
	global_load_dwordx4 v[22:25], v[22:23], off nt
	s_mov_b32 s1, 0x430000
	v_add_co_u32_e32 v36, vcc, s1, v40
	s_mov_b32 s1, 0x438000
	s_nop 0
	v_addc_co_u32_e32 v37, vcc, 0, v41, vcc
	global_load_dwordx4 v[36:39], v[36:37], off nt
	v_add_co_u32_e32 v40, vcc, s1, v40
	v_lshl_add_u64 v[44:45], s[94:95], 1, v[30:31]
	s_nop 0
	v_addc_co_u32_e32 v41, vcc, 0, v41, vcc
	global_load_dwordx4 v[40:43], v[40:41], off nt
	s_waitcnt vmcnt(7)
	ds_write2_b32 v50, v2, v3 offset1:1
	ds_write2_b32 v50, v4, v5 offset0:2 offset1:3
	s_waitcnt vmcnt(6)
	ds_write2_b32 v51, v6, v7 offset1:1
	ds_write2_b32 v52, v8, v9 offset1:1
	s_waitcnt vmcnt(5)
	ds_write2_b32 v53, v10, v11 offset1:1
	ds_write2_b32 v54, v12, v13 offset1:1
	s_waitcnt vmcnt(4)
	ds_write2_b32 v55, v14, v15 offset1:1
	ds_write2_b32 v56, v16, v17 offset1:1
	s_waitcnt vmcnt(3)
	ds_write2_b32 v57, v18, v19 offset1:1
	ds_write2_b32 v58, v20, v21 offset1:1
	s_waitcnt vmcnt(2)
	ds_write2_b32 v59, v22, v23 offset1:1
	ds_write2_b32 v60, v24, v25 offset1:1
	s_waitcnt vmcnt(1)
	ds_write2_b32 v61, v36, v37 offset1:1
	ds_write2_b32 v62, v38, v39 offset1:1
	s_waitcnt vmcnt(0)
	ds_write2_b32 v63, v40, v41 offset1:1
	ds_write2_b32 v64, v42, v43 offset1:1
	s_waitcnt lgkmcnt(0)
	ds_read2_b32 v[6:7], v49 offset0:33 offset1:41
	ds_read2_b32 v[8:9], v49 offset1:8
	ds_read2_b32 v[10:11], v49 offset0:66 offset1:74
	ds_read2_b32 v[12:13], v49 offset0:99 offset1:107
	ds_read2_b32 v[14:15], v49 offset0:132 offset1:140
	ds_read2_b32 v[16:17], v49 offset0:165 offset1:173
	ds_read2_b32 v[18:19], v49 offset0:198 offset1:206
	ds_read2_b32 v[20:21], v49 offset0:231 offset1:239
	s_waitcnt lgkmcnt(5)
	v_bfe_u32 v3, v10, 16, 1
	s_waitcnt lgkmcnt(3)
	v_bfe_u32 v5, v14, 16, 1
	v_bfe_u32 v0, v8, 16, 1
	v_bfe_u32 v2, v6, 16, 1
	v_bfe_u32 v4, v12, 16, 1
	s_waitcnt lgkmcnt(2)
	v_bfe_u32 v22, v16, 16, 1
	v_add3_u32 v3, v10, v3, s58
	v_add3_u32 v5, v14, v5, s58
	s_waitcnt lgkmcnt(1)
	v_bfe_u32 v23, v18, 16, 1
	v_add3_u32 v0, v8, v0, s58
	v_add3_u32 v2, v6, v2, s58
	v_add3_u32 v4, v12, v4, s58
	v_add3_u32 v6, v16, v22, s58
	v_lshrrev_b32_e32 v3, 16, v3
	v_lshrrev_b32_e32 v5, 16, v5
	v_add3_u32 v8, v18, v23, s58
	v_lshrrev_b32_e32 v0, 16, v0
	v_and_or_b32 v3, v4, s59, v3
	v_and_or_b32 v4, v6, s59, v5
	s_waitcnt lgkmcnt(0)
	v_bfe_u32 v5, v20, 16, 1
	v_and_or_b32 v2, v2, s59, v0
	v_lshrrev_b32_e32 v0, 16, v8
	v_add3_u32 v5, v20, v5, s58
	v_and_or_b32 v5, v5, s59, v0
	v_or_b32_e32 v0, s0, v29
	v_lshlrev_b32_e32 v0, 11, v0
	v_lshl_add_u64 v[22:23], v[44:45], 0, v[0:1]
	v_bfe_u32 v0, v9, 16, 1
	global_store_dwordx4 v[22:23], v[2:5], off
	v_add3_u32 v0, v9, v0, s58
	v_lshrrev_b32_e32 v0, 16, v0
	v_bfe_u32 v2, v7, 16, 1
	v_add3_u32 v2, v7, v2, s58
	v_and_or_b32 v2, v2, s59, v0
	v_bfe_u32 v0, v11, 16, 1
	v_add3_u32 v0, v11, v0, s58
	v_bfe_u32 v3, v13, 16, 1
	v_lshrrev_b32_e32 v0, 16, v0
	v_add3_u32 v3, v13, v3, s58
	v_and_or_b32 v3, v3, s59, v0
	v_bfe_u32 v0, v15, 16, 1
	v_add3_u32 v0, v15, v0, s58
	v_bfe_u32 v4, v17, 16, 1
	v_lshrrev_b32_e32 v0, 16, v0
	v_add3_u32 v4, v17, v4, s58
	v_and_or_b32 v4, v4, s59, v0
	v_bfe_u32 v0, v19, 16, 1
	v_add3_u32 v0, v19, v0, s58
	v_bfe_u32 v5, v21, 16, 1
	v_lshrrev_b32_e32 v0, 16, v0
	v_add3_u32 v5, v21, v5, s58
	v_and_or_b32 v5, v5, s59, v0
	v_or_b32_e32 v0, s0, v46
	v_lshlrev_b32_e32 v0, 11, v0
	ds_read2_b32 v[6:7], v49 offset0:16 offset1:24
	v_lshl_add_u64 v[8:9], v[44:45], 0, v[0:1]
	global_store_dwordx4 v[8:9], v[2:5], off
	ds_read2_b32 v[8:9], v49 offset0:49 offset1:57
	ds_read2_b32 v[10:11], v49 offset0:82 offset1:90
	ds_read2_b32 v[12:13], v49 offset0:115 offset1:123
	s_waitcnt lgkmcnt(3)
	v_bfe_u32 v0, v6, 16, 1
	v_add3_u32 v0, v6, v0, s58
	s_waitcnt lgkmcnt(2)
	v_bfe_u32 v2, v8, 16, 1
	ds_read2_b32 v[14:15], v49 offset0:148 offset1:156
	v_lshrrev_b32_e32 v0, 16, v0
	v_add3_u32 v2, v8, v2, s58
	ds_read2_b32 v[16:17], v49 offset0:181 offset1:189
	v_and_or_b32 v2, v2, s59, v0
	s_waitcnt lgkmcnt(3)
	v_bfe_u32 v0, v10, 16, 1
	v_add3_u32 v0, v10, v0, s58
	s_waitcnt lgkmcnt(2)
	v_bfe_u32 v3, v12, 16, 1
	ds_read2_b32 v[18:19], v49 offset0:214 offset1:222
	v_lshrrev_b32_e32 v0, 16, v0
	v_add3_u32 v3, v12, v3, s58
	ds_read2_b32 v[20:21], v49 offset0:247 offset1:255
	v_and_or_b32 v3, v3, s59, v0
	s_waitcnt lgkmcnt(3)
	v_bfe_u32 v0, v14, 16, 1
	v_add3_u32 v0, v14, v0, s58
	s_waitcnt lgkmcnt(2)
	v_bfe_u32 v4, v16, 16, 1
	v_lshrrev_b32_e32 v0, 16, v0
	v_add3_u32 v4, v16, v4, s58
	v_and_or_b32 v4, v4, s59, v0
	s_waitcnt lgkmcnt(1)
	v_bfe_u32 v0, v18, 16, 1
	v_add3_u32 v0, v18, v0, s58
	s_waitcnt lgkmcnt(0)
	v_bfe_u32 v5, v20, 16, 1
	v_lshrrev_b32_e32 v0, 16, v0
	v_add3_u32 v5, v20, v5, s58
	v_and_or_b32 v5, v5, s59, v0
	v_or_b32_e32 v0, s0, v47
	v_lshlrev_b32_e32 v0, 11, v0
	v_lshl_add_u64 v[22:23], v[44:45], 0, v[0:1]
	v_bfe_u32 v0, v7, 16, 1
	global_store_dwordx4 v[22:23], v[2:5], off
	v_add3_u32 v0, v7, v0, s58
	v_lshrrev_b32_e32 v0, 16, v0
	v_bfe_u32 v2, v9, 16, 1
	v_add3_u32 v2, v9, v2, s58
	v_and_or_b32 v2, v2, s59, v0
	v_bfe_u32 v0, v11, 16, 1
	v_add3_u32 v0, v11, v0, s58
	v_bfe_u32 v3, v13, 16, 1
	v_lshrrev_b32_e32 v0, 16, v0
	v_add3_u32 v3, v13, v3, s58
	v_and_or_b32 v3, v3, s59, v0
	v_bfe_u32 v0, v15, 16, 1
	v_add3_u32 v0, v15, v0, s58
	v_bfe_u32 v4, v17, 16, 1
	v_lshrrev_b32_e32 v0, 16, v0
	v_add3_u32 v4, v17, v4, s58
	v_and_or_b32 v4, v4, s59, v0
	v_bfe_u32 v0, v19, 16, 1
	v_add3_u32 v0, v19, v0, s58
	v_bfe_u32 v5, v21, 16, 1
	v_lshrrev_b32_e32 v0, 16, v0
	v_add3_u32 v5, v21, v5, s58
	v_and_or_b32 v5, v5, s59, v0
	v_or_b32_e32 v0, s0, v48
	v_lshlrev_b32_e32 v0, 11, v0
	v_lshl_add_u64 v[6:7], v[44:45], 0, v[0:1]
	global_store_dwordx4 v[6:7], v[2:5], off
	s_waitcnt lgkmcnt(0)

; #define LAS __attribute__((address_space(3)))
; #define LDS_WAIT() asm volatile("s_waitcnt lgkmcnt(0)" ::: "memory")
; __device__ __forceinline__ unsigned pk2(float lo, float hi) { return f2bf(lo) | (f2bf(hi) << 16); }
; #define ARG_IN(i) argp(i)
; __device__ __forceinline__ void transpose_item(const float* __restrict__ W, int ldw, int k0, int c0, bf16* WT, int K, int drow0, LAS float* scr, int lane) {
;     { const int kr = lane >> 3, n4 = lane & 7;
;       f32x4 v[8];
; #pragma unroll
;       for (int i = 0; i < 8; ++i) v[i] = *(const f32x4*)(W + (size_t)(k0 + 8 * i + kr) * ldw + c0 + 4 * n4);
; #pragma unroll
;       for (int i = 0; i < 8; ++i) { LAS float* p = scr + (8 * i + kr) * 33 + 4 * n4; p[0] = v[i].x; p[1] = v[i].y; p[2] = v[i].z; p[3] = v[i].w; } }
;     LDS_WAIT(); asm volatile("" ::: "memory");
;     const int c = lane & 7;
; #pragma unroll
;     for (int j = 0; j < 4; ++j) { const int n = (lane >> 3) + 8 * j; const LAS float* s = scr + (8 * c) * 33 + n;
;         v4u o; o.x = pk2(s[0 * 33], s[1 * 33]); o.y = pk2(s[2 * 33], s[3 * 33]); o.z = pk2(s[4 * 33], s[5 * 33]); o.w = pk2(s[6 * 33], s[7 * 33]);
;         *(v4u*)(WT + (size_t)(drow0 + n) * K + k0 + 8 * c) = o; }
; __device__ __forceinline__ void weights_phase(int l, LAS unsigned char* lds, int vcu, int G, int wave, int lane) {
;     ...
;         } else if ((r -= IT_IN) < IT_BR) { const int n = (r / 256) * 2; r %= 256; const int kb = r / 32, nb = r % 32;
;             transpose_item(ARG_IN(14) + (size_t)(l * 3 + n) * 512 * 1024, 1024, 64 * kb, 32 * nb, WBR, 512, n * 1024 + 32 * nb, scr, lane);
.LBB0_195:
	s_andn2_b64 vcc, exec, s[10:11]
	s_cbranch_vccnz .LBB0_197
	s_add_i32 s0, s3, 0xffffce00
	s_lshr_b32 s0, s0, 7
	s_and_b32 s12, s0, 0x1fffffe
	s_add_i32 s94, s12, 3
	s_lshl_b64 s[10:11], s[94:95], 21
	s_load_dwordx2 s[0:1], s[96:97], 0x70
	s_waitcnt lgkmcnt(0)
	s_add_u32 s10, s0, s10
	s_addc_u32 s1, s1, s11
	s_lshl_b32 s0, s3, 1
	s_and_b32 s13, s0, 0x1c0
	s_lshl_b32 s0, s3, 5
	s_and_b32 s11, s0, 0x3e0
	s_lshl_b32 s0, s12, 10
	s_or_b32 s0, s0, s11
	s_lshl_b32 s11, s11, 2
	s_add_u32 s10, s10, s11
	v_or_b32_e32 v4, s13, v29
	s_addc_u32 s11, s1, 0
	v_lshlrev_b32_e32 v0, 2, v26
	v_lshl_add_u64 v[2:3], s[10:11], 0, v[0:1]
	v_lshlrev_b32_e32 v0, 12, v4
	v_lshl_add_u64 v[40:41], v[2:3], 0, v[0:1]
	s_mov_b32 s1, 0x8000
	v_add_co_u32_e32 v6, vcc, s1, v40
	s_mov_b32 s1, 0x10000
	s_nop 0
	v_addc_co_u32_e32 v7, vcc, 0, v41, vcc
	v_add_co_u32_e32 v10, vcc, s1, v40
	s_mov_b32 s1, 0x18000
	s_nop 0
	v_addc_co_u32_e32 v11, vcc, 0, v41, vcc
	v_add_co_u32_e32 v14, vcc, s1, v40
	s_mov_b32 s1, 0x20000
	s_nop 0
	v_addc_co_u32_e32 v15, vcc, 0, v41, vcc
	v_add_co_u32_e32 v18, vcc, s1, v40
	s_mov_b32 s1, 0x28000
	s_nop 0
	v_addc_co_u32_e32 v19, vcc, 0, v41, vcc
	v_add_co_u32_e32 v22, vcc, s1, v40
	global_load_dwordx4 v[2:5], v[40:41], off nt
	s_nop 0
	global_load_dwordx4 v[6:9], v[6:7], off nt
	v_addc_co_u32_e32 v23, vcc, 0, v41, vcc
	global_load_dwordx4 v[10:13], v[10:11], off nt
	s_nop 0
	global_load_dwordx4 v[14:17], v[14:15], off nt
	s_nop 0
	global_load_dwordx4 v[18:21], v[18:19], off nt
	s_nop 0
	global_load_dwordx4 v[22:25], v[22:23], off nt
	s_mov_b32 s1, 0x30000
	v_add_co_u32_e32 v36, vcc, s1, v40
	s_mov_b32 s1, 0x38000
	s_nop 0
	v_addc_co_u32_e32 v37, vcc, 0, v41, vcc
	global_load_dwordx4 v[36:39], v[36:37], off nt
	v_add_co_u32_e32 v40, vcc, s1, v40
	s_lshl_b32 s94, s13, 1
	s_nop 0
	v_addc_co_u32_e32 v41, vcc, 0, v41, vcc
	global_load_dwordx4 v[40:43], v[40:41], off nt
	v_lshl_add_u64 v[44:45], v[32:33], 0, s[94:95]
	s_waitcnt vmcnt(7)
	ds_write2_b32 v50, v2, v3 offset1:1
	ds_write2_b32 v50, v4, v5 offset0:2 offset1:3
	s_waitcnt vmcnt(6)
	ds_write2_b32 v51, v6, v7 offset1:1
	ds_write2_b32 v52, v8, v9 offset1:1
	s_waitcnt vmcnt(5)
	ds_write2_b32 v53, v10, v11 offset1:1
	ds_write2_b32 v54, v12, v13 offset1:1
	s_waitcnt vmcnt(4)
	ds_write2_b32 v55, v14, v15 offset1:1
	ds_write2_b32 v56, v16, v17 offset1:1
	s_waitcnt vmcnt(3)
	ds_write2_b32 v57, v18, v19 offset1:1
	ds_write2_b32 v58, v20, v21 offset1:1
	s_waitcnt vmcnt(2)
	ds_write2_b32 v59, v22, v23 offset1:1
	ds_write2_b32 v60, v24, v25 offset1:1
	s_waitcnt vmcnt(1)
	ds_write2_b32 v61, v36, v37 offset1:1
	ds_write2_b32 v62, v38, v39 offset1:1
	s_waitcnt vmcnt(0)
	ds_write2_b32 v63, v40, v41 offset1:1
	ds_write2_b32 v64, v42, v43 offset1:1
	s_waitcnt lgkmcnt(0)
	ds_read2_b32 v[6:7], v49 offset0:33 offset1:41
	ds_read2_b32 v[8:9], v49 offset1:8
	ds_read2_b32 v[10:11], v49 offset0:66 offset1:74
	ds_read2_b32 v[12:13], v49 offset0:99 offset1:107
	ds_read2_b32 v[14:15], v49 offset0:132 offset1:140
	ds_read2_b32 v[16:17], v49 offset0:165 offset1:173
	ds_read2_b32 v[18:19], v49 offset0:198 offset1:206
	ds_read2_b32 v[20:21], v49 offset0:231 offset1:239
	s_waitcnt lgkmcnt(5)
	v_bfe_u32 v3, v10, 16, 1
	s_waitcnt lgkmcnt(3)
	v_bfe_u32 v5, v14, 16, 1
	v_bfe_u32 v0, v8, 16, 1
	v_bfe_u32 v2, v6, 16, 1
	v_bfe_u32 v4, v12, 16, 1
	s_waitcnt lgkmcnt(2)
	v_bfe_u32 v22, v16, 16, 1
	v_add3_u32 v3, v10, v3, s58
	v_add3_u32 v5, v14, v5, s58
	s_waitcnt lgkmcnt(1)
; #define LAS __attribute__((address_space(3)))
; #define LDS_WAIT() asm volatile("s_waitcnt lgkmcnt(0)" ::: "memory")
; __device__ __forceinline__ unsigned pk2(float lo, float hi) { return f2bf(lo) | (f2bf(hi) << 16); }
; __device__ __forceinline__ void transpose_item(const float* __restrict__ W, int ldw, int k0, int c0, bf16* WT, int K, int drow0, LAS float* scr, int lane) {
;     ...
;     const int c = lane & 7;
; #pragma unroll
;     for (int j = 0; j < 4; ++j) { const int n = (lane >> 3) + 8 * j; const LAS float* s = scr + (8 * c) * 33 + n;
;         v4u o; o.x = pk2(s[0 * 33], s[1 * 33]); o.y = pk2(s[2 * 33], s[3 * 33]); o.z = pk2(s[4 * 33], s[5 * 33]); o.w = pk2(s[6 * 33], s[7 * 33]);
;         *(v4u*)(WT + (size_t)(drow0 + n) * K + k0 + 8 * c) = o; }
;     LDS_WAIT(); asm volatile("" ::: "memory");
	v_bfe_u32 v23, v18, 16, 1
	v_add3_u32 v0, v8, v0, s58
	v_add3_u32 v2, v6, v2, s58
	v_add3_u32 v4, v12, v4, s58
	v_add3_u32 v6, v16, v22, s58
	v_lshrrev_b32_e32 v3, 16, v3
	v_lshrrev_b32_e32 v5, 16, v5
	v_add3_u32 v8, v18, v23, s58
	v_lshrrev_b32_e32 v0, 16, v0
	v_and_or_b32 v3, v4, s59, v3
	v_and_or_b32 v4, v6, s59, v5
	s_waitcnt lgkmcnt(0)
	v_bfe_u32 v5, v20, 16, 1
	v_and_or_b32 v2, v2, s59, v0
	v_lshrrev_b32_e32 v0, 16, v8
	v_add3_u32 v5, v20, v5, s58
	v_and_or_b32 v5, v5, s59, v0
	v_or_b32_e32 v0, s0, v29
	v_lshlrev_b32_e32 v0, 10, v0
	v_lshl_add_u64 v[22:23], v[44:45], 0, v[0:1]
	v_bfe_u32 v0, v9, 16, 1
	global_store_dwordx4 v[22:23], v[2:5], off
	v_add3_u32 v0, v9, v0, s58
	v_lshrrev_b32_e32 v0, 16, v0
	v_bfe_u32 v2, v7, 16, 1
	v_add3_u32 v2, v7, v2, s58
	v_and_or_b32 v2, v2, s59, v0
	v_bfe_u32 v0, v11, 16, 1
	v_add3_u32 v0, v11, v0, s58
	v_bfe_u32 v3, v13, 16, 1
	v_lshrrev_b32_e32 v0, 16, v0
	v_add3_u32 v3, v13, v3, s58
	v_and_or_b32 v3, v3, s59, v0
	v_bfe_u32 v0, v15, 16, 1
	v_add3_u32 v0, v15, v0, s58
	v_bfe_u32 v4, v17, 16, 1
	v_lshrrev_b32_e32 v0, 16, v0
	v_add3_u32 v4, v17, v4, s58
	v_and_or_b32 v4, v4, s59, v0
	v_bfe_u32 v0, v19, 16, 1
	v_add3_u32 v0, v19, v0, s58
	v_bfe_u32 v5, v21, 16, 1
	v_lshrrev_b32_e32 v0, 16, v0
	v_add3_u32 v5, v21, v5, s58
	v_and_or_b32 v5, v5, s59, v0
	v_or_b32_e32 v0, s0, v46
	v_lshlrev_b32_e32 v0, 10, v0
	ds_read2_b32 v[6:7], v49 offset0:16 offset1:24
	v_lshl_add_u64 v[8:9], v[44:45], 0, v[0:1]
	global_store_dwordx4 v[8:9], v[2:5], off
	ds_read2_b32 v[8:9], v49 offset0:49 offset1:57
	ds_read2_b32 v[10:11], v49 offset0:82 offset1:90
	ds_read2_b32 v[12:13], v49 offset0:115 offset1:123
	s_waitcnt lgkmcnt(3)
	v_bfe_u32 v0, v6, 16, 1
	v_add3_u32 v0, v6, v0, s58
	s_waitcnt lgkmcnt(2)
	v_bfe_u32 v2, v8, 16, 1
	ds_read2_b32 v[14:15], v49 offset0:148 offset1:156
	v_lshrrev_b32_e32 v0, 16, v0
	v_add3_u32 v2, v8, v2, s58
	ds_read2_b32 v[16:17], v49 offset0:181 offset1:189
	v_and_or_b32 v2, v2, s59, v0
	s_waitcnt lgkmcnt(3)
	v_bfe_u32 v0, v10, 16, 1
	v_add3_u32 v0, v10, v0, s58
	s_waitcnt lgkmcnt(2)
	v_bfe_u32 v3, v12, 16, 1
	ds_read2_b32 v[18:19], v49 offset0:214 offset1:222
	v_lshrrev_b32_e32 v0, 16, v0
	v_add3_u32 v3, v12, v3, s58
	ds_read2_b32 v[20:21], v49 offset0:247 offset1:255
	v_and_or_b32 v3, v3, s59, v0
	s_waitcnt lgkmcnt(3)
	v_bfe_u32 v0, v14, 16, 1
	v_add3_u32 v0, v14, v0, s58
	s_waitcnt lgkmcnt(2)
	v_bfe_u32 v4, v16, 16, 1
	v_lshrrev_b32_e32 v0, 16, v0
	v_add3_u32 v4, v16, v4, s58
	v_and_or_b32 v4, v4, s59, v0
	s_waitcnt lgkmcnt(1)
	v_bfe_u32 v0, v18, 16, 1
	v_add3_u32 v0, v18, v0, s58
	s_waitcnt lgkmcnt(0)
	v_bfe_u32 v5, v20, 16, 1
	v_lshrrev_b32_e32 v0, 16, v0
	v_add3_u32 v5, v20, v5, s58
	v_and_or_b32 v5, v5, s59, v0
	v_or_b32_e32 v0, s0, v47
	v_lshlrev_b32_e32 v0, 10, v0
	v_lshl_add_u64 v[22:23], v[44:45], 0, v[0:1]
	v_bfe_u32 v0, v7, 16, 1
	global_store_dwordx4 v[22:23], v[2:5], off
	v_add3_u32 v0, v7, v0, s58
	v_lshrrev_b32_e32 v0, 16, v0
	v_bfe_u32 v2, v9, 16, 1
	v_add3_u32 v2, v9, v2, s58
	v_and_or_b32 v2, v2, s59, v0
	v_bfe_u32 v0, v11, 16, 1
	v_add3_u32 v0, v11, v0, s58
	v_bfe_u32 v3, v13, 16, 1
	v_lshrrev_b32_e32 v0, 16, v0
	v_add3_u32 v3, v13, v3, s58
	v_and_or_b32 v3, v3, s59, v0
	v_bfe_u32 v0, v15, 16, 1
	v_add3_u32 v0, v15, v0, s58
	v_bfe_u32 v4, v17, 16, 1
	v_lshrrev_b32_e32 v0, 16, v0
	v_add3_u32 v4, v17, v4, s58
	v_and_or_b32 v4, v4, s59, v0
	v_bfe_u32 v0, v19, 16, 1
	v_add3_u32 v0, v19, v0, s58
	v_bfe_u32 v5, v21, 16, 1
	v_lshrrev_b32_e32 v0, 16, v0
	v_add3_u32 v5, v21, v5, s58
	v_and_or_b32 v5, v5, s59, v0
	v_or_b32_e32 v0, s0, v48
	v_lshlrev_b32_e32 v0, 10, v0
	v_lshl_add_u64 v[6:7], v[44:45], 0, v[0:1]
	global_store_dwordx4 v[6:7], v[2:5], off
	s_waitcnt lgkmcnt(0)

; #define LAS __attribute__((address_space(3)))
; #define LDS_WAIT() asm volatile("s_waitcnt lgkmcnt(0)" ::: "memory")
; __device__ __forceinline__ unsigned pk2(float lo, float hi) { return f2bf(lo) | (f2bf(hi) << 16); }
; #define ARG_IN(i) argp(i)
; __device__ __forceinline__ void transpose_item(const float* __restrict__ W, int ldw, int k0, int c0, bf16* WT, int K, int drow0, LAS float* scr, int lane) {
;     { const int kr = lane >> 3, n4 = lane & 7;
;       f32x4 v[8];
; #pragma unroll
;       for (int i = 0; i < 8; ++i) v[i] = *(const f32x4*)(W + (size_t)(k0 + 8 * i + kr) * ldw + c0 + 4 * n4);
; #pragma unroll
;       for (int i = 0; i < 8; ++i) { LAS float* p = scr + (8 * i + kr) * 33 + 4 * n4; p[0] = v[i].x; p[1] = v[i].y; p[2] = v[i].z; p[3] = v[i].w; } }
;     LDS_WAIT(); asm volatile("" ::: "memory");
;     const int c = lane & 7;
; #pragma unroll
;     for (int j = 0; j < 4; ++j) { const int n = (lane >> 3) + 8 * j; const LAS float* s = scr + (8 * c) * 33 + n;
;         v4u o; o.x = pk2(s[0 * 33], s[1 * 33]); o.y = pk2(s[2 * 33], s[3 * 33]); o.z = pk2(s[4 * 33], s[5 * 33]); o.w = pk2(s[6 * 33], s[7 * 33]);
;         *(v4u*)(WT + (size_t)(drow0 + n) * K + k0 + 8 * c) = o; }
; __device__ __forceinline__ void weights_phase(int l, LAS unsigned char* lds, int vcu, int G, int wave, int lane) {
;     ...
;         } else if ((r -= IT_DN) < IT_IN) { const int kb = r / 208, nb = r % 208, L0 = 32 * nb, c0 = L0 < 3584 ? L0 : L0 + 8, pn = L0 >> 8, w = L0 & 255, hh = w >> 6, dh = (w >> 5) & 1;
;             transpose_item(ARG_IN(8) + (size_t)l * 1024 * DIN, DIN, 64 * kb, c0, WIN, 1024, 256 * pn + 128 * dh + 32 * hh, scr, lane);
.LBB0_198:
	s_andn2_b64 vcc, exec, s[10:11]
	s_cbranch_vccnz .LBB0_200
	s_add_i32 s0, s3, 0xdb00
	s_and_b32 s1, s0, 0xffff
	s_mulk_i32 s1, 0x4ec5
	s_lshr_b32 s12, s1, 16
	s_lshr_b32 s1, s1, 22
	s_mulk_i32 s1, 0xd0
	s_sub_i32 s0, s0, s1
	s_and_b32 s0, s0, 0xffff
	s_lshl_b32 s1, s0, 5
	s_or_b32 s10, s1, 8
	s_cmpk_lt_u32 s0, 0x70
	s_cselect_b32 s13, s1, s10
	s_lshl_b32 s14, s0, 7
	s_and_b32 s1, s1, 0x1f00
	s_and_b32 s14, s14, 0x80
	s_lshl_b32 s0, s0, 4
	s_or_b32 s1, s1, s14
	s_and_b32 s0, s0, 0x60
	s_load_dwordx2 s[10:11], s[96:97], 64
	s_waitcnt lgkmcnt(0)
	s_and_b32 s12, s12, 0x7fc0
	s_or_b32 s0, s1, s0
	s_lshl_b32 s1, s13, 2
	s_add_u32 s10, s10, s1
	v_or_b32_e32 v4, s12, v29
	s_addc_u32 s11, s11, 0
	v_lshlrev_b32_e32 v0, 2, v26
	v_lshl_add_u64 v[2:3], s[10:11], 0, v[0:1]
	v_mul_u32_u24_e32 v0, 0x1a08, v4
	v_lshlrev_b32_e32 v0, 2, v0
	v_lshl_add_u64 v[40:41], v[2:3], 0, v[0:1]
	s_mov_b32 s1, 0x1a08000
	v_add_co_u32_e32 v2, vcc, s1, v40
	s_mov_b32 s1, 0x1a3c000
	s_nop 0
	v_addc_co_u32_e32 v3, vcc, 0, v41, vcc
	v_add_co_u32_e32 v6, vcc, s1, v40
	s_mov_b32 s1, 0x1a70000
	s_nop 0
	v_addc_co_u32_e32 v7, vcc, 0, v41, vcc
	v_add_co_u32_e32 v10, vcc, s1, v40
	s_mov_b32 s1, 0x1aa4000
	s_nop 0
	v_addc_co_u32_e32 v11, vcc, 0, v41, vcc
	v_add_co_u32_e32 v14, vcc, s1, v40
	s_mov_b32 s1, 0x1ad8000
	s_nop 0
	v_addc_co_u32_e32 v15, vcc, 0, v41, vcc
	v_add_co_u32_e32 v18, vcc, s1, v40
	s_mov_b32 s1, 0x1b0c000
	s_nop 0
	v_addc_co_u32_e32 v19, vcc, 0, v41, vcc
	v_add_co_u32_e32 v22, vcc, s1, v40
	global_load_dwordx4 v[2:5], v[2:3], off nt
	s_nop 0
	global_load_dwordx4 v[6:9], v[6:7], off offset:256 nt
	v_addc_co_u32_e32 v23, vcc, 0, v41, vcc
	global_load_dwordx4 v[10:13], v[10:11], off offset:512 nt
	s_nop 0
	global_load_dwordx4 v[14:17], v[14:15], off offset:768 nt
	s_nop 0
	global_load_dwordx4 v[18:21], v[18:19], off offset:1024 nt
	s_nop 0
	global_load_dwordx4 v[22:25], v[22:23], off offset:1280 nt
	s_mov_b32 s1, 0x1b40000
	v_add_co_u32_e32 v36, vcc, s1, v40
	s_mov_b32 s1, 0x1b74000
	s_nop 0
	v_addc_co_u32_e32 v37, vcc, 0, v41, vcc
	global_load_dwordx4 v[36:39], v[36:37], off offset:1536 nt
	v_add_co_u32_e32 v40, vcc, s1, v40
	s_lshl_b32 s94, s12, 1
	s_nop 0
	v_addc_co_u32_e32 v41, vcc, 0, v41, vcc
	global_load_dwordx4 v[40:43], v[40:41], off offset:1792 nt
	v_lshl_add_u64 v[44:45], v[34:35], 0, s[94:95]
	s_waitcnt vmcnt(7)
	ds_write2_b32 v50, v2, v3 offset1:1
	ds_write2_b32 v50, v4, v5 offset0:2 offset1:3
	s_waitcnt vmcnt(6)
	ds_write2_b32 v51, v6, v7 offset1:1
	ds_write2_b32 v52, v8, v9 offset1:1
	s_waitcnt vmcnt(5)
	ds_write2_b32 v53, v10, v11 offset1:1
	ds_write2_b32 v54, v12, v13 offset1:1
	s_waitcnt vmcnt(4)
	ds_write2_b32 v55, v14, v15 offset1:1
	ds_write2_b32 v56, v16, v17 offset1:1
	s_waitcnt vmcnt(3)
	ds_write2_b32 v57, v18, v19 offset1:1
	ds_write2_b32 v58, v20, v21 offset1:1
	s_waitcnt vmcnt(2)
	ds_write2_b32 v59, v22, v23 offset1:1
	ds_write2_b32 v60, v24, v25 offset1:1
	s_waitcnt vmcnt(1)
	ds_write2_b32 v61, v36, v37 offset1:1
	ds_write2_b32 v62, v38, v39 offset1:1
	s_waitcnt vmcnt(0)
	ds_write2_b32 v63, v40, v41 offset1:1
	ds_write2_b32 v64, v42, v43 offset1:1
	s_waitcnt lgkmcnt(0)
	ds_read2_b32 v[6:7], v49 offset0:33 offset1:41
	ds_read2_b32 v[8:9], v49 offset1:8
	ds_read2_b32 v[10:11], v49 offset0:66 offset1:74
	ds_read2_b32 v[12:13], v49 offset0:99 offset1:107
	ds_read2_b32 v[14:15], v49 offset0:132 offset1:140
	ds_read2_b32 v[16:17], v49 offset0:165 offset1:173
	s_waitcnt lgkmcnt(4)
	v_bfe_u32 v0, v8, 16, 1
	ds_read2_b32 v[18:19], v49 offset0:198 offset1:206
	v_bfe_u32 v2, v6, 16, 1
	v_add3_u32 v0, v8, v0, s58
	ds_read2_b32 v[20:21], v49 offset0:231 offset1:239
	s_waitcnt lgkmcnt(5)
	v_bfe_u32 v3, v10, 16, 1
	s_waitcnt lgkmcnt(3)
; #define LAS __attribute__((address_space(3)))
; #define LDS_WAIT() asm volatile("s_waitcnt lgkmcnt(0)" ::: "memory")
; __device__ __forceinline__ unsigned pk2(float lo, float hi) { return f2bf(lo) | (f2bf(hi) << 16); }
; __device__ __forceinline__ void transpose_item(const float* __restrict__ W, int ldw, int k0, int c0, bf16* WT, int K, int drow0, LAS float* scr, int lane) {
;     ...
;     const int c = lane & 7;
; #pragma unroll
;     for (int j = 0; j < 4; ++j) { const int n = (lane >> 3) + 8 * j; const LAS float* s = scr + (8 * c) * 33 + n;
;         v4u o; o.x = pk2(s[0 * 33], s[1 * 33]); o.y = pk2(s[2 * 33], s[3 * 33]); o.z = pk2(s[4 * 33], s[5 * 33]); o.w = pk2(s[6 * 33], s[7 * 33]);
;         *(v4u*)(WT + (size_t)(drow0 + n) * K + k0 + 8 * c) = o; }
;     LDS_WAIT(); asm volatile("" ::: "memory");
	v_bfe_u32 v5, v14, 16, 1
	v_add3_u32 v2, v6, v2, s58
	v_lshrrev_b32_e32 v0, 16, v0
	v_bfe_u32 v4, v12, 16, 1
	v_add3_u32 v3, v10, v3, s58
	v_add3_u32 v5, v14, v5, s58
	v_and_or_b32 v2, v2, s59, v0
	s_waitcnt lgkmcnt(2)
	v_bfe_u32 v0, v16, 16, 1
	v_add3_u32 v4, v12, v4, s58
	v_lshrrev_b32_e32 v3, 16, v3
	v_lshrrev_b32_e32 v5, 16, v5
	v_add3_u32 v0, v16, v0, s58
	v_and_or_b32 v3, v4, s59, v3
	v_and_or_b32 v4, v0, s59, v5
	s_waitcnt lgkmcnt(1)
	v_bfe_u32 v0, v18, 16, 1
	v_add3_u32 v0, v18, v0, s58
	s_waitcnt lgkmcnt(0)
	v_bfe_u32 v5, v20, 16, 1
	v_lshrrev_b32_e32 v0, 16, v0
	v_add3_u32 v5, v20, v5, s58
	v_and_or_b32 v5, v5, s59, v0
	v_or_b32_e32 v0, s0, v29
	v_lshlrev_b32_e32 v0, 11, v0
	v_lshl_add_u64 v[22:23], v[44:45], 0, v[0:1]
	v_bfe_u32 v0, v9, 16, 1
	global_store_dwordx4 v[22:23], v[2:5], off
	v_add3_u32 v0, v9, v0, s58
	v_lshrrev_b32_e32 v0, 16, v0
	v_bfe_u32 v2, v7, 16, 1
	v_add3_u32 v2, v7, v2, s58
	v_and_or_b32 v2, v2, s59, v0
	v_bfe_u32 v0, v11, 16, 1
	v_add3_u32 v0, v11, v0, s58
	v_bfe_u32 v3, v13, 16, 1
	v_lshrrev_b32_e32 v0, 16, v0
	v_add3_u32 v3, v13, v3, s58
	v_and_or_b32 v3, v3, s59, v0
	v_bfe_u32 v0, v15, 16, 1
	v_add3_u32 v0, v15, v0, s58
	v_bfe_u32 v4, v17, 16, 1
	v_lshrrev_b32_e32 v0, 16, v0
	v_add3_u32 v4, v17, v4, s58
	v_and_or_b32 v4, v4, s59, v0
	v_bfe_u32 v0, v19, 16, 1
	v_add3_u32 v0, v19, v0, s58
	v_bfe_u32 v5, v21, 16, 1
	v_lshrrev_b32_e32 v0, 16, v0
	v_add3_u32 v5, v21, v5, s58
	v_and_or_b32 v5, v5, s59, v0
	v_or_b32_e32 v0, s0, v46
	v_lshlrev_b32_e32 v0, 11, v0
	ds_read2_b32 v[6:7], v49 offset0:16 offset1:24
	v_lshl_add_u64 v[8:9], v[44:45], 0, v[0:1]
	global_store_dwordx4 v[8:9], v[2:5], off
	ds_read2_b32 v[8:9], v49 offset0:49 offset1:57
	ds_read2_b32 v[10:11], v49 offset0:82 offset1:90
	ds_read2_b32 v[12:13], v49 offset0:115 offset1:123
	s_waitcnt lgkmcnt(3)
	v_bfe_u32 v0, v6, 16, 1
	v_add3_u32 v0, v6, v0, s58
	s_waitcnt lgkmcnt(2)
	v_bfe_u32 v2, v8, 16, 1
	ds_read2_b32 v[14:15], v49 offset0:148 offset1:156
	v_lshrrev_b32_e32 v0, 16, v0
	v_add3_u32 v2, v8, v2, s58
	ds_read2_b32 v[16:17], v49 offset0:181 offset1:189
	v_and_or_b32 v2, v2, s59, v0
	s_waitcnt lgkmcnt(3)
	v_bfe_u32 v0, v10, 16, 1
	v_add3_u32 v0, v10, v0, s58
	s_waitcnt lgkmcnt(2)
	v_bfe_u32 v3, v12, 16, 1
	ds_read2_b32 v[18:19], v49 offset0:214 offset1:222
	v_lshrrev_b32_e32 v0, 16, v0
	v_add3_u32 v3, v12, v3, s58
	ds_read2_b32 v[20:21], v49 offset0:247 offset1:255
	v_and_or_b32 v3, v3, s59, v0
	s_waitcnt lgkmcnt(3)
	v_bfe_u32 v0, v14, 16, 1
	v_add3_u32 v0, v14, v0, s58
	s_waitcnt lgkmcnt(2)
	v_bfe_u32 v4, v16, 16, 1
	v_lshrrev_b32_e32 v0, 16, v0
	v_add3_u32 v4, v16, v4, s58
	v_and_or_b32 v4, v4, s59, v0
	s_waitcnt lgkmcnt(1)
	v_bfe_u32 v0, v18, 16, 1
	v_add3_u32 v0, v18, v0, s58
	s_waitcnt lgkmcnt(0)
	v_bfe_u32 v5, v20, 16, 1
	v_lshrrev_b32_e32 v0, 16, v0
	v_add3_u32 v5, v20, v5, s58
	v_and_or_b32 v5, v5, s59, v0
	v_or_b32_e32 v0, s0, v47
	v_lshlrev_b32_e32 v0, 11, v0
	v_lshl_add_u64 v[22:23], v[44:45], 0, v[0:1]
	v_bfe_u32 v0, v7, 16, 1
	global_store_dwordx4 v[22:23], v[2:5], off
	v_add3_u32 v0, v7, v0, s58
	v_lshrrev_b32_e32 v0, 16, v0
	v_bfe_u32 v2, v9, 16, 1
	v_add3_u32 v2, v9, v2, s58
	v_and_or_b32 v2, v2, s59, v0
	v_bfe_u32 v0, v11, 16, 1
	v_add3_u32 v0, v11, v0, s58
	v_bfe_u32 v3, v13, 16, 1
	v_lshrrev_b32_e32 v0, 16, v0
	v_add3_u32 v3, v13, v3, s58
	v_and_or_b32 v3, v3, s59, v0
	v_bfe_u32 v0, v15, 16, 1
	v_add3_u32 v0, v15, v0, s58
	v_bfe_u32 v4, v17, 16, 1
	v_lshrrev_b32_e32 v0, 16, v0
	v_add3_u32 v4, v17, v4, s58
	v_and_or_b32 v4, v4, s59, v0
	v_bfe_u32 v0, v19, 16, 1
	v_add3_u32 v0, v19, v0, s58
	v_bfe_u32 v5, v21, 16, 1
	v_lshrrev_b32_e32 v0, 16, v0
	v_add3_u32 v5, v21, v5, s58
	v_and_or_b32 v5, v5, s59, v0
	v_or_b32_e32 v0, s0, v48
	v_lshlrev_b32_e32 v0, 11, v0
	v_lshl_add_u64 v[6:7], v[44:45], 0, v[0:1]
	global_store_dwordx4 v[6:7], v[2:5], off
	s_waitcnt lgkmcnt(0)

; #define LAS __attribute__((address_space(3)))
; #define LDS_WAIT() asm volatile("s_waitcnt lgkmcnt(0)" ::: "memory")
; __device__ __forceinline__ unsigned pk2(float lo, float hi) { return f2bf(lo) | (f2bf(hi) << 16); }
; #define ARG_IN(i) argp(i)
; __device__ __forceinline__ void transpose_item(const float* __restrict__ W, int ldw, int k0, int c0, bf16* WT, int K, int drow0, LAS float* scr, int lane) {
;     { const int kr = lane >> 3, n4 = lane & 7;
;       f32x4 v[8];
; #pragma unroll
;       for (int i = 0; i < 8; ++i) v[i] = *(const f32x4*)(W + (size_t)(k0 + 8 * i + kr) * ldw + c0 + 4 * n4);
; #pragma unroll
;       for (int i = 0; i < 8; ++i) { LAS float* p = scr + (8 * i + kr) * 33 + 4 * n4; p[0] = v[i].x; p[1] = v[i].y; p[2] = v[i].z; p[3] = v[i].w; } }
;     LDS_WAIT(); asm volatile("" ::: "memory");
;     const int c = lane & 7;
; #pragma unroll
;     for (int j = 0; j < 4; ++j) { const int n = (lane >> 3) + 8 * j; const LAS float* s = scr + (8 * c) * 33 + n;
;         v4u o; o.x = pk2(s[0 * 33], s[1 * 33]); o.y = pk2(s[2 * 33], s[3 * 33]); o.z = pk2(s[4 * 33], s[5 * 33]); o.w = pk2(s[6 * 33], s[7 * 33]);
;         *(v4u*)(WT + (size_t)(drow0 + n) * K + k0 + 8 * c) = o; }
; __device__ __forceinline__ void weights_phase(int l, LAS unsigned char* lds, int vcu, int G, int wave, int lane) {
;     ...
;         } else if ((r -= IT_GU) < IT_DN) { const int j = r / 1408; r %= 1408; const int kb = r / 32, nb = r % 32;
;             transpose_item(ARG_IN(7) + (size_t)(l * 2 + j) * 2816 * 1024, 1024, 64 * kb, 32 * nb, WD + (size_t)j * 1024 * 2816, 2816, 32 * nb, scr, lane);
.LBB0_201:
	s_andn2_b64 vcc, exec, s[10:11]
	s_cbranch_vccnz .LBB0_203
	s_add_i32 s0, s3, 0xffffe600
	s_add_i32 s1, s3, 0xffffe080
	s_cmpk_lt_u32 s0, 0x580
	s_cselect_b32 s10, s0, s1
	s_cmpk_gt_u32 s0, 0x57f
	s_mov_b32 s11, 0x2100000
	s_cselect_b32 s11, s11, 0x1600000
	s_load_dwordx2 s[0:1], s[96:97], 56
	s_waitcnt lgkmcnt(0)
	s_cselect_b32 s12, 0x580000, 0
	s_add_u32 s11, s0, s11
	s_addc_u32 s1, s1, 0
	s_lshl_b32 s0, s10, 1
	s_and_b32 s13, s0, 0xfc0
	s_lshl_b32 s0, s10, 5
	s_and_b32 s0, s0, 0x3e0
	s_add_u32 s12, s20, s12
	s_addc_u32 s14, s21, 0
	s_lshl_b32 s10, s0, 2
	s_add_u32 s10, s11, s10
	v_or_b32_e32 v4, s13, v29
	s_addc_u32 s11, s1, 0
	v_lshlrev_b32_e32 v0, 2, v26
	v_lshl_add_u64 v[2:3], s[10:11], 0, v[0:1]
	v_lshlrev_b32_e32 v0, 12, v4
	v_lshl_add_u64 v[40:41], v[2:3], 0, v[0:1]
	s_mov_b32 s1, 0x8000
	v_add_co_u32_e32 v6, vcc, s1, v40
	s_mov_b32 s1, 0x10000
	s_nop 0
	v_addc_co_u32_e32 v7, vcc, 0, v41, vcc
	v_add_co_u32_e32 v10, vcc, s1, v40
	s_mov_b32 s1, 0x18000
	s_nop 0
	v_addc_co_u32_e32 v11, vcc, 0, v41, vcc
	v_add_co_u32_e32 v14, vcc, s1, v40
	s_mov_b32 s1, 0x20000
	s_nop 0
	v_addc_co_u32_e32 v15, vcc, 0, v41, vcc
	v_add_co_u32_e32 v18, vcc, s1, v40
	s_mov_b32 s1, 0x28000
	s_nop 0
	v_addc_co_u32_e32 v19, vcc, 0, v41, vcc
	v_add_co_u32_e32 v22, vcc, s1, v40
	global_load_dwordx4 v[2:5], v[40:41], off nt
	s_nop 0
	global_load_dwordx4 v[6:9], v[6:7], off nt
	v_addc_co_u32_e32 v23, vcc, 0, v41, vcc
	global_load_dwordx4 v[10:13], v[10:11], off nt
	s_nop 0
	global_load_dwordx4 v[14:17], v[14:15], off nt
	s_nop 0
	global_load_dwordx4 v[18:21], v[18:19], off nt
	s_nop 0
	global_load_dwordx4 v[22:25], v[22:23], off nt
	s_mov_b32 s1, 0x30000
	v_add_co_u32_e32 v36, vcc, s1, v40
	s_mov_b32 s1, 0x38000
	s_nop 0
	v_addc_co_u32_e32 v37, vcc, 0, v41, vcc
	global_load_dwordx4 v[36:39], v[36:37], off nt
	v_add_co_u32_e32 v40, vcc, s1, v40
	s_lshl_b32 s1, s13, 1
	s_nop 0
	v_addc_co_u32_e32 v41, vcc, 0, v41, vcc
	global_load_dwordx4 v[40:43], v[40:41], off nt
	s_add_u32 s10, s12, s1
	s_addc_u32 s11, s14, 0
	v_lshlrev_b32_e32 v0, 1, v28
	v_lshl_add_u64 v[44:45], s[10:11], 0, v[0:1]
	s_waitcnt vmcnt(7)
	ds_write2_b32 v50, v2, v3 offset1:1
	ds_write2_b32 v50, v4, v5 offset0:2 offset1:3
	s_waitcnt vmcnt(6)
	ds_write2_b32 v51, v6, v7 offset1:1
	ds_write2_b32 v52, v8, v9 offset1:1
	s_waitcnt vmcnt(5)
	ds_write2_b32 v53, v10, v11 offset1:1
	ds_write2_b32 v54, v12, v13 offset1:1
	s_waitcnt vmcnt(4)
	ds_write2_b32 v55, v14, v15 offset1:1
	ds_write2_b32 v56, v16, v17 offset1:1
	s_waitcnt vmcnt(3)
	ds_write2_b32 v57, v18, v19 offset1:1
	ds_write2_b32 v58, v20, v21 offset1:1
	s_waitcnt vmcnt(2)
	ds_write2_b32 v59, v22, v23 offset1:1
	ds_write2_b32 v60, v24, v25 offset1:1
	s_waitcnt vmcnt(1)
	ds_write2_b32 v61, v36, v37 offset1:1
	ds_write2_b32 v62, v38, v39 offset1:1
	s_waitcnt vmcnt(0)
	ds_write2_b32 v63, v40, v41 offset1:1
	ds_write2_b32 v64, v42, v43 offset1:1
	s_waitcnt lgkmcnt(0)
	ds_read2_b32 v[6:7], v49 offset0:33 offset1:41
	ds_read2_b32 v[8:9], v49 offset1:8
	ds_read2_b32 v[10:11], v49 offset0:66 offset1:74
	ds_read2_b32 v[12:13], v49 offset0:99 offset1:107
	ds_read2_b32 v[14:15], v49 offset0:132 offset1:140
	ds_read2_b32 v[16:17], v49 offset0:165 offset1:173
	ds_read2_b32 v[18:19], v49 offset0:198 offset1:206
	s_waitcnt lgkmcnt(5)
	v_bfe_u32 v0, v8, 16, 1
	v_bfe_u32 v2, v6, 16, 1
	v_add3_u32 v0, v8, v0, s58
	s_waitcnt lgkmcnt(1)
	v_bfe_u32 v20, v16, 16, 1
	v_add3_u32 v2, v6, v2, s58
	v_lshrrev_b32_e32 v0, 16, v0
	v_and_or_b32 v2, v2, s59, v0
	v_add3_u32 v0, v16, v20, s58
	ds_read2_b32 v[20:21], v49 offset0:231 offset1:239
	v_bfe_u32 v3, v10, 16, 1
	v_bfe_u32 v5, v14, 16, 1
	v_bfe_u32 v4, v12, 16, 1
	v_add3_u32 v3, v10, v3, s58
	v_add3_u32 v5, v14, v5, s58
	v_add3_u32 v4, v12, v4, s58
	v_lshrrev_b32_e32 v3, 16, v3
	v_lshrrev_b32_e32 v5, 16, v5
	v_and_or_b32 v3, v4, s59, v3
	v_and_or_b32 v4, v0, s59, v5
	s_waitcnt lgkmcnt(1)
; #define LAS __attribute__((address_space(3)))
; #define LDS_WAIT() asm volatile("s_waitcnt lgkmcnt(0)" ::: "memory")
; __device__ __forceinline__ unsigned pk2(float lo, float hi) { return f2bf(lo) | (f2bf(hi) << 16); }
; __device__ __forceinline__ void transpose_item(const float* __restrict__ W, int ldw, int k0, int c0, bf16* WT, int K, int drow0, LAS float* scr, int lane) {
;     ...
;     const int c = lane & 7;
; #pragma unroll
;     for (int j = 0; j < 4; ++j) { const int n = (lane >> 3) + 8 * j; const LAS float* s = scr + (8 * c) * 33 + n;
;         v4u o; o.x = pk2(s[0 * 33], s[1 * 33]); o.y = pk2(s[2 * 33], s[3 * 33]); o.z = pk2(s[4 * 33], s[5 * 33]); o.w = pk2(s[6 * 33], s[7 * 33]);
;         *(v4u*)(WT + (size_t)(drow0 + n) * K + k0 + 8 * c) = o; }
;     LDS_WAIT(); asm volatile("" ::: "memory");
	v_bfe_u32 v0, v18, 16, 1
	v_add3_u32 v0, v18, v0, s58
	s_waitcnt lgkmcnt(0)
	v_bfe_u32 v5, v20, 16, 1
	v_lshrrev_b32_e32 v0, 16, v0
	v_add3_u32 v5, v20, v5, s58
	v_and_or_b32 v5, v5, s59, v0
	v_or_b32_e32 v0, s0, v29
	v_mul_u32_u24_e32 v0, 0xb00, v0
	v_lshlrev_b32_e32 v0, 1, v0
	v_lshl_add_u64 v[22:23], v[44:45], 0, v[0:1]
	v_bfe_u32 v0, v9, 16, 1
	global_store_dwordx4 v[22:23], v[2:5], off
	v_add3_u32 v0, v9, v0, s58
	v_lshrrev_b32_e32 v0, 16, v0
	v_bfe_u32 v2, v7, 16, 1
	v_add3_u32 v2, v7, v2, s58
	v_and_or_b32 v2, v2, s59, v0
	v_bfe_u32 v0, v11, 16, 1
	v_add3_u32 v0, v11, v0, s58
	v_bfe_u32 v3, v13, 16, 1
	v_lshrrev_b32_e32 v0, 16, v0
	v_add3_u32 v3, v13, v3, s58
	v_and_or_b32 v3, v3, s59, v0
	v_bfe_u32 v0, v15, 16, 1
	v_add3_u32 v0, v15, v0, s58
	v_bfe_u32 v4, v17, 16, 1
	v_lshrrev_b32_e32 v0, 16, v0
	v_add3_u32 v4, v17, v4, s58
	v_and_or_b32 v4, v4, s59, v0
	v_bfe_u32 v0, v19, 16, 1
	v_add3_u32 v0, v19, v0, s58
	v_bfe_u32 v5, v21, 16, 1
	v_lshrrev_b32_e32 v0, 16, v0
	v_add3_u32 v5, v21, v5, s58
	v_and_or_b32 v5, v5, s59, v0
	v_or_b32_e32 v0, s0, v46
	v_mul_u32_u24_e32 v0, 0xb00, v0
	v_lshlrev_b32_e32 v0, 1, v0
	ds_read2_b32 v[6:7], v49 offset0:16 offset1:24
	v_lshl_add_u64 v[8:9], v[44:45], 0, v[0:1]
	global_store_dwordx4 v[8:9], v[2:5], off
	ds_read2_b32 v[8:9], v49 offset0:49 offset1:57
	ds_read2_b32 v[10:11], v49 offset0:82 offset1:90
	ds_read2_b32 v[12:13], v49 offset0:115 offset1:123
	s_waitcnt lgkmcnt(3)
	v_bfe_u32 v0, v6, 16, 1
	v_add3_u32 v0, v6, v0, s58
	s_waitcnt lgkmcnt(2)
	v_bfe_u32 v2, v8, 16, 1
	ds_read2_b32 v[14:15], v49 offset0:148 offset1:156
	v_lshrrev_b32_e32 v0, 16, v0
	v_add3_u32 v2, v8, v2, s58
	ds_read2_b32 v[16:17], v49 offset0:181 offset1:189
	v_and_or_b32 v2, v2, s59, v0
	s_waitcnt lgkmcnt(3)
	v_bfe_u32 v0, v10, 16, 1
	v_add3_u32 v0, v10, v0, s58
	s_waitcnt lgkmcnt(2)
	v_bfe_u32 v3, v12, 16, 1
	ds_read2_b32 v[18:19], v49 offset0:214 offset1:222
	v_lshrrev_b32_e32 v0, 16, v0
	v_add3_u32 v3, v12, v3, s58
	ds_read2_b32 v[20:21], v49 offset0:247 offset1:255
	v_and_or_b32 v3, v3, s59, v0
	s_waitcnt lgkmcnt(3)
	v_bfe_u32 v0, v14, 16, 1
	v_add3_u32 v0, v14, v0, s58
	s_waitcnt lgkmcnt(2)
	v_bfe_u32 v4, v16, 16, 1
	v_lshrrev_b32_e32 v0, 16, v0
	v_add3_u32 v4, v16, v4, s58
	v_and_or_b32 v4, v4, s59, v0
	s_waitcnt lgkmcnt(1)
	v_bfe_u32 v0, v18, 16, 1
	v_add3_u32 v0, v18, v0, s58
	s_waitcnt lgkmcnt(0)
	v_bfe_u32 v5, v20, 16, 1
	v_lshrrev_b32_e32 v0, 16, v0
	v_add3_u32 v5, v20, v5, s58
	v_and_or_b32 v5, v5, s59, v0
	v_or_b32_e32 v0, s0, v47
	v_mul_u32_u24_e32 v0, 0xb00, v0
	v_lshlrev_b32_e32 v0, 1, v0
	v_lshl_add_u64 v[22:23], v[44:45], 0, v[0:1]
	v_bfe_u32 v0, v7, 16, 1
	global_store_dwordx4 v[22:23], v[2:5], off
	v_add3_u32 v0, v7, v0, s58
	v_lshrrev_b32_e32 v0, 16, v0
	v_bfe_u32 v2, v9, 16, 1
	v_add3_u32 v2, v9, v2, s58
	v_and_or_b32 v2, v2, s59, v0
	v_bfe_u32 v0, v11, 16, 1
	v_add3_u32 v0, v11, v0, s58
	v_bfe_u32 v3, v13, 16, 1
	v_lshrrev_b32_e32 v0, 16, v0
	v_add3_u32 v3, v13, v3, s58
	v_and_or_b32 v3, v3, s59, v0
	v_bfe_u32 v0, v15, 16, 1
	v_add3_u32 v0, v15, v0, s58
	v_bfe_u32 v4, v17, 16, 1
	v_lshrrev_b32_e32 v0, 16, v0
	v_add3_u32 v4, v17, v4, s58
	v_and_or_b32 v4, v4, s59, v0
	v_bfe_u32 v0, v19, 16, 1
	v_add3_u32 v0, v19, v0, s58
	v_bfe_u32 v5, v21, 16, 1
	v_lshrrev_b32_e32 v0, 16, v0
	v_add3_u32 v5, v21, v5, s58
	v_and_or_b32 v5, v5, s59, v0
	v_or_b32_e32 v0, s0, v48
	v_mul_u32_u24_e32 v0, 0xb00, v0
	v_lshlrev_b32_e32 v0, 1, v0
	v_lshl_add_u64 v[6:7], v[44:45], 0, v[0:1]
	global_store_dwordx4 v[6:7], v[2:5], off
	s_waitcnt lgkmcnt(0)

; #define LAS __attribute__((address_space(3)))
; #define LDS_WAIT() asm volatile("s_waitcnt lgkmcnt(0)" ::: "memory")
; __device__ __forceinline__ unsigned pk2(float lo, float hi) { return f2bf(lo) | (f2bf(hi) << 16); }
; #define ARG_IN(i) argp(i)
; __device__ __forceinline__ void transpose_item(const float* __restrict__ W, int ldw, int k0, int c0, bf16* WT, int K, int drow0, LAS float* scr, int lane) {
;     { const int kr = lane >> 3, n4 = lane & 7;
;       f32x4 v[8];
; #pragma unroll
;       for (int i = 0; i < 8; ++i) v[i] = *(const f32x4*)(W + (size_t)(k0 + 8 * i + kr) * ldw + c0 + 4 * n4);
; #pragma unroll
;       for (int i = 0; i < 8; ++i) { LAS float* p = scr + (8 * i + kr) * 33 + 4 * n4; p[0] = v[i].x; p[1] = v[i].y; p[2] = v[i].z; p[3] = v[i].w; } }
;     LDS_WAIT(); asm volatile("" ::: "memory");
;     const int c = lane & 7;
; #pragma unroll
;     for (int j = 0; j < 4; ++j) { const int n = (lane >> 3) + 8 * j; const LAS float* s = scr + (8 * c) * 33 + n;
;         v4u o; o.x = pk2(s[0 * 33], s[1 * 33]); o.y = pk2(s[2 * 33], s[3 * 33]); o.z = pk2(s[4 * 33], s[5 * 33]); o.w = pk2(s[6 * 33], s[7 * 33]);
;         *(v4u*)(WT + (size_t)(drow0 + n) * K + k0 + 8 * c) = o; }
; __device__ __forceinline__ void weights_phase(int l, LAS unsigned char* lds, int vcu, int G, int wave, int lane) {
;     ...
;         } else if ((r -= IT_EFF) < IT_GU) { const int j = r / 2816; r %= 2816; const int isup = r / 1408; r %= 1408; const int kb = r / 88, nb = r % 88, f0 = 32 * nb;
;             const float* src = (isup ? ARG_IN(6) : ARG_IN(5)) + (size_t)(l * 2 + j) * 1024 * 2816;
;             transpose_item(src, 2816, 64 * kb, f0, WGU + (size_t)j * NGU * 1024, 1024, 256 * (f0 >> 7) + 128 * isup + (f0 & 127), scr, lane);
.LBB0_209:
	s_mul_hi_u32 s12, s1, 0xba2e8ba3
	s_lshr_b32 s12, s12, 10
	s_mul_i32 s13, s12, 0x580
	s_sub_i32 s1, s1, s13
	s_mul_i32 s13, s1, 0xba2f
	s_lshr_b32 s14, s13, 16
	s_lshr_b32 s13, s13, 22
	s_mulk_i32 s13, 0x58
	s_sub_i32 s1, s1, s13
	s_and_b32 s1, s1, 0xffff
	s_lshl_b32 s13, s1, 5
	s_cmpk_gt_u32 s0, 0xaff
	s_mov_b32 s0, 0x2100000
	s_cselect_b32 s0, s0, 0x1600000
	s_cselect_b32 s15, 0xb00000, 0
	s_add_u32 s10, s10, s0
	s_addc_u32 s11, s11, 0
	s_and_b32 s14, s14, 0xffc0
	s_add_u32 s15, s18, s15
	s_addc_u32 s16, s19, 0
	s_lshl_b32 s0, s1, 6
	s_and_b32 s0, s0, 0x1f00
	s_lshl_b32 s12, s12, 7
	s_add_i32 s0, s0, s12
	s_and_b32 s12, s13, 0x60
	s_or_b32 s0, s0, s12
	s_lshl_b32 s1, s1, 7
	s_add_u32 s10, s10, s1
	v_or_b32_e32 v4, s14, v29
	s_addc_u32 s11, s11, 0
	v_lshlrev_b32_e32 v0, 2, v26
	v_lshl_add_u64 v[2:3], s[10:11], 0, v[0:1]
	v_mul_u32_u24_e32 v0, 0xb00, v4
	v_lshlrev_b32_e32 v0, 2, v0
	v_lshl_add_u64 v[40:41], v[2:3], 0, v[0:1]
	s_mov_b32 s1, 0x16000
	v_add_co_u32_e32 v6, vcc, s1, v40
	s_mov_b32 s1, 0x2c000
	s_nop 0
	v_addc_co_u32_e32 v7, vcc, 0, v41, vcc
	v_add_co_u32_e32 v10, vcc, s1, v40
	s_mov_b32 s1, 0x42000
	s_nop 0
	v_addc_co_u32_e32 v11, vcc, 0, v41, vcc
	v_add_co_u32_e32 v14, vcc, s1, v40
	s_mov_b32 s1, 0x58000
	s_nop 0
	v_addc_co_u32_e32 v15, vcc, 0, v41, vcc
	v_add_co_u32_e32 v18, vcc, s1, v40
	s_mov_b32 s1, 0x6e000
	s_nop 0
	v_addc_co_u32_e32 v19, vcc, 0, v41, vcc
	v_add_co_u32_e32 v22, vcc, s1, v40
	global_load_dwordx4 v[2:5], v[40:41], off nt
	s_nop 0
	global_load_dwordx4 v[6:9], v[6:7], off nt
	v_addc_co_u32_e32 v23, vcc, 0, v41, vcc
	global_load_dwordx4 v[10:13], v[10:11], off nt
	s_nop 0
	global_load_dwordx4 v[14:17], v[14:15], off nt
	s_nop 0
	global_load_dwordx4 v[18:21], v[18:19], off nt
	s_nop 0
	global_load_dwordx4 v[22:25], v[22:23], off nt
	s_mov_b32 s1, 0x84000
	v_add_co_u32_e32 v36, vcc, s1, v40
	s_mov_b32 s1, 0x9a000
	s_nop 0
	v_addc_co_u32_e32 v37, vcc, 0, v41, vcc
	global_load_dwordx4 v[36:39], v[36:37], off nt
	v_add_co_u32_e32 v40, vcc, s1, v40
	s_lshl_b32 s1, s14, 1
	s_nop 0
	v_addc_co_u32_e32 v41, vcc, 0, v41, vcc
	global_load_dwordx4 v[40:43], v[40:41], off nt
	s_add_u32 s10, s15, s1
	s_addc_u32 s11, s16, 0
	v_lshlrev_b32_e32 v0, 1, v28
	v_lshl_add_u64 v[44:45], s[10:11], 0, v[0:1]
	s_waitcnt vmcnt(7)
	ds_write2_b32 v50, v2, v3 offset1:1
	ds_write2_b32 v50, v4, v5 offset0:2 offset1:3
	s_waitcnt vmcnt(6)
	ds_write2_b32 v51, v6, v7 offset1:1
	ds_write2_b32 v52, v8, v9 offset1:1
	s_waitcnt vmcnt(5)
	ds_write2_b32 v53, v10, v11 offset1:1
	ds_write2_b32 v54, v12, v13 offset1:1
	s_waitcnt vmcnt(4)
	ds_write2_b32 v55, v14, v15 offset1:1
	ds_write2_b32 v56, v16, v17 offset1:1
	s_waitcnt vmcnt(3)
	ds_write2_b32 v57, v18, v19 offset1:1
	ds_write2_b32 v58, v20, v21 offset1:1
	s_waitcnt vmcnt(2)
	ds_write2_b32 v59, v22, v23 offset1:1
	ds_write2_b32 v60, v24, v25 offset1:1
	s_waitcnt vmcnt(1)
	ds_write2_b32 v61, v36, v37 offset1:1
	ds_write2_b32 v62, v38, v39 offset1:1
	s_waitcnt vmcnt(0)
	ds_write2_b32 v63, v40, v41 offset1:1
	ds_write2_b32 v64, v42, v43 offset1:1
	s_waitcnt lgkmcnt(0)
	ds_read2_b32 v[6:7], v49 offset0:33 offset1:41
	ds_read2_b32 v[8:9], v49 offset1:8
	ds_read2_b32 v[10:11], v49 offset0:66 offset1:74
	ds_read2_b32 v[12:13], v49 offset0:99 offset1:107
	ds_read2_b32 v[14:15], v49 offset0:132 offset1:140
	ds_read2_b32 v[16:17], v49 offset0:165 offset1:173
	ds_read2_b32 v[18:19], v49 offset0:198 offset1:206
	s_waitcnt lgkmcnt(5)
	v_bfe_u32 v0, v8, 16, 1
	v_bfe_u32 v2, v6, 16, 1
	v_add3_u32 v0, v8, v0, s58
	s_waitcnt lgkmcnt(1)
; #define LAS __attribute__((address_space(3)))
; #define LDS_WAIT() asm volatile("s_waitcnt lgkmcnt(0)" ::: "memory")
; __device__ __forceinline__ unsigned pk2(float lo, float hi) { return f2bf(lo) | (f2bf(hi) << 16); }
; __device__ __forceinline__ void transpose_item(const float* __restrict__ W, int ldw, int k0, int c0, bf16* WT, int K, int drow0, LAS float* scr, int lane) {
;     ...
;     const int c = lane & 7;
; #pragma unroll
;     for (int j = 0; j < 4; ++j) { const int n = (lane >> 3) + 8 * j; const LAS float* s = scr + (8 * c) * 33 + n;
;         v4u o; o.x = pk2(s[0 * 33], s[1 * 33]); o.y = pk2(s[2 * 33], s[3 * 33]); o.z = pk2(s[4 * 33], s[5 * 33]); o.w = pk2(s[6 * 33], s[7 * 33]);
;         *(v4u*)(WT + (size_t)(drow0 + n) * K + k0 + 8 * c) = o; }
;     LDS_WAIT(); asm volatile("" ::: "memory");
	v_bfe_u32 v20, v16, 16, 1
	v_add3_u32 v2, v6, v2, s58
	v_lshrrev_b32_e32 v0, 16, v0
	v_and_or_b32 v2, v2, s59, v0
	v_add3_u32 v0, v16, v20, s58
	ds_read2_b32 v[20:21], v49 offset0:231 offset1:239
	v_bfe_u32 v3, v10, 16, 1
	v_bfe_u32 v5, v14, 16, 1
	v_bfe_u32 v4, v12, 16, 1
	v_add3_u32 v3, v10, v3, s58
	v_add3_u32 v5, v14, v5, s58
	v_add3_u32 v4, v12, v4, s58
	v_lshrrev_b32_e32 v3, 16, v3
	v_lshrrev_b32_e32 v5, 16, v5
	v_and_or_b32 v3, v4, s59, v3
	v_and_or_b32 v4, v0, s59, v5
	s_waitcnt lgkmcnt(1)
	v_bfe_u32 v0, v18, 16, 1
	v_add3_u32 v0, v18, v0, s58
	s_waitcnt lgkmcnt(0)
	v_bfe_u32 v5, v20, 16, 1
	v_lshrrev_b32_e32 v0, 16, v0
	v_add3_u32 v5, v20, v5, s58
	v_and_or_b32 v5, v5, s59, v0
	v_or_b32_e32 v0, s0, v29
	v_lshlrev_b32_e32 v0, 11, v0
	v_lshl_add_u64 v[22:23], v[44:45], 0, v[0:1]
	v_bfe_u32 v0, v9, 16, 1
	global_store_dwordx4 v[22:23], v[2:5], off
	v_add3_u32 v0, v9, v0, s58
	v_lshrrev_b32_e32 v0, 16, v0
	v_bfe_u32 v2, v7, 16, 1
	v_add3_u32 v2, v7, v2, s58
	v_and_or_b32 v2, v2, s59, v0
	v_bfe_u32 v0, v11, 16, 1
	v_add3_u32 v0, v11, v0, s58
	v_bfe_u32 v3, v13, 16, 1
	v_lshrrev_b32_e32 v0, 16, v0
	v_add3_u32 v3, v13, v3, s58
	v_and_or_b32 v3, v3, s59, v0
	v_bfe_u32 v0, v15, 16, 1
	v_add3_u32 v0, v15, v0, s58
	v_bfe_u32 v4, v17, 16, 1
	v_lshrrev_b32_e32 v0, 16, v0
	v_add3_u32 v4, v17, v4, s58
	v_and_or_b32 v4, v4, s59, v0
	v_bfe_u32 v0, v19, 16, 1
	v_add3_u32 v0, v19, v0, s58
	v_bfe_u32 v5, v21, 16, 1
	v_lshrrev_b32_e32 v0, 16, v0
	v_add3_u32 v5, v21, v5, s58
	v_and_or_b32 v5, v5, s59, v0
	v_or_b32_e32 v0, s0, v46
	v_lshlrev_b32_e32 v0, 11, v0
	ds_read2_b32 v[6:7], v49 offset0:16 offset1:24
	v_lshl_add_u64 v[8:9], v[44:45], 0, v[0:1]
	global_store_dwordx4 v[8:9], v[2:5], off
	ds_read2_b32 v[8:9], v49 offset0:49 offset1:57
	ds_read2_b32 v[10:11], v49 offset0:82 offset1:90
	ds_read2_b32 v[12:13], v49 offset0:115 offset1:123
	s_waitcnt lgkmcnt(3)
	v_bfe_u32 v0, v6, 16, 1
	v_add3_u32 v0, v6, v0, s58
	s_waitcnt lgkmcnt(2)
	v_bfe_u32 v2, v8, 16, 1
	ds_read2_b32 v[14:15], v49 offset0:148 offset1:156
	v_lshrrev_b32_e32 v0, 16, v0
	v_add3_u32 v2, v8, v2, s58
	ds_read2_b32 v[16:17], v49 offset0:181 offset1:189
	v_and_or_b32 v2, v2, s59, v0
	s_waitcnt lgkmcnt(3)
	v_bfe_u32 v0, v10, 16, 1
	v_add3_u32 v0, v10, v0, s58
	s_waitcnt lgkmcnt(2)
	v_bfe_u32 v3, v12, 16, 1
	ds_read2_b32 v[18:19], v49 offset0:214 offset1:222
	v_lshrrev_b32_e32 v0, 16, v0
	v_add3_u32 v3, v12, v3, s58
	ds_read2_b32 v[20:21], v49 offset0:247 offset1:255
	v_and_or_b32 v3, v3, s59, v0
	s_waitcnt lgkmcnt(3)
	v_bfe_u32 v0, v14, 16, 1
	v_add3_u32 v0, v14, v0, s58
	s_waitcnt lgkmcnt(2)
	v_bfe_u32 v4, v16, 16, 1
	v_lshrrev_b32_e32 v0, 16, v0
	v_add3_u32 v4, v16, v4, s58
	v_and_or_b32 v4, v4, s59, v0
	s_waitcnt lgkmcnt(1)
	v_bfe_u32 v0, v18, 16, 1
	v_add3_u32 v0, v18, v0, s58
	s_waitcnt lgkmcnt(0)
	v_bfe_u32 v5, v20, 16, 1
	v_lshrrev_b32_e32 v0, 16, v0
	v_add3_u32 v5, v20, v5, s58
	v_and_or_b32 v5, v5, s59, v0
	v_or_b32_e32 v0, s0, v47
	v_lshlrev_b32_e32 v0, 11, v0
	v_lshl_add_u64 v[22:23], v[44:45], 0, v[0:1]
	v_bfe_u32 v0, v7, 16, 1
	global_store_dwordx4 v[22:23], v[2:5], off
	v_add3_u32 v0, v7, v0, s58
	v_lshrrev_b32_e32 v0, 16, v0
	v_bfe_u32 v2, v9, 16, 1
	v_add3_u32 v2, v9, v2, s58
	v_and_or_b32 v2, v2, s59, v0
	v_bfe_u32 v0, v11, 16, 1
	v_add3_u32 v0, v11, v0, s58
	v_bfe_u32 v3, v13, 16, 1
	v_lshrrev_b32_e32 v0, 16, v0
	v_add3_u32 v3, v13, v3, s58
	v_and_or_b32 v3, v3, s59, v0
	v_bfe_u32 v0, v15, 16, 1
	v_add3_u32 v0, v15, v0, s58
	v_bfe_u32 v4, v17, 16, 1
	v_lshrrev_b32_e32 v0, 16, v0
	v_add3_u32 v4, v17, v4, s58
	v_and_or_b32 v4, v4, s59, v0
	v_bfe_u32 v0, v19, 16, 1
	v_add3_u32 v0, v19, v0, s58
	v_bfe_u32 v5, v21, 16, 1
	v_lshrrev_b32_e32 v0, 16, v0
	v_add3_u32 v5, v21, v5, s58
	v_and_or_b32 v5, v5, s59, v0
	v_or_b32_e32 v0, s0, v48
	v_lshlrev_b32_e32 v0, 11, v0
	v_lshl_add_u64 v[6:7], v[44:45], 0, v[0:1]
	global_store_dwordx4 v[6:7], v[2:5], off
	s_waitcnt lgkmcnt(0)
